# EpiMerge (G2) epilogue rewritten too: gate loads batched 8 pairs deep, counted vmcnt
# speedup vs baseline: 1.0419x; 1.0419x over previous
; #define G8_STAGE(bufoff, gbase, voff) do { _Pragma("unroll") for (int _i = 0; _i < 2; ++_i) \
;     __builtin_amdgcn_global_load_lds((const unsigned*)((const char*)(gbase) + (voff)[_i]), (LAS unsigned*)(lds + (bufoff) + ldsw + _i * 8192), 16, 0, 0); } while (0)
; #define G8_LDA(dst, b, h) do { _Pragma("unroll") for (int m = 0; m < 4; ++m) _Pragma("unroll") for (int k = 0; k < 2; ++k) dst[m][k] = *(const LAS bf16x8*)(lds + G8_SA(b, h) + aoff + m * 2048 + k * 1024); } while (0)
; #define G8_LDB(dst, b, h) do { _Pragma("unroll") for (int n = 0; n < 2; ++n) _Pragma("unroll") for (int k = 0; k < 2; ++k) dst[n][k] = *(const LAS bf16x8*)(lds + G8_SB(b, h) + boff + n * 2048 + k * 1024); } while (0)
; #define G8_MMA(ai, bj, At, Bt) do { __builtin_amdgcn_s_setprio(1); _Pragma("unroll") for (int m = 0; m < 4; ++m) _Pragma("unroll") for (int n = 0; n < 2; ++n) _Pragma("unroll") for (int k = 0; k < 2; ++k) \
;     acc[ai][bj][m][n] = __builtin_amdgcn_mfma_f32_16x16x32_bf16(Bt[n][k], At[m][k], acc[ai][bj][m][n], 0, 0, 0); __builtin_amdgcn_s_setprio(0); } while (0)
; #define G8_WAIT_L(n) asm volatile("s_waitcnt lgkmcnt(" #n ")" ::: "memory")
; #define G8_BAR __builtin_amdgcn_s_barrier()
; #define G8_SCHED __builtin_amdgcn_sched_barrier(0)
; template <class Epi, class Sched>
; __device__ __forceinline__ void gemm_phase(const int wv_, LAS unsigned char* lds, const int lda, const int ldb, const int K, const Sched& S, const Epi& E) {
;     ...
;       G8_LDB(B0, 0, 0); G8_SCHED; G8_LDA(At, 0, 0); G8_STAGE(G8_SA(1, 1), a1 + hstepA, voffA);
;       G8_WAIT_L(8); G8_BAR; G8_WAIT_L(0); G8_MMA(0, 0, At, B0); G8_BAR; G8_SCHED;
;       G8_LDB(B1, 0, 1); G8_STAGE(G8_SB(0, 0), b2, voffB);
;       G8_BAR; G8_WAIT_L(0); G8_MMA(0, 1, At, B1); G8_BAR;
;       G8_LDA(At, 0, 1); G8_STAGE(G8_SA(0, 0), a2, voffA);
;       G8_BAR; G8_WAIT_L(0); G8_MMA(1, 0, At, B0); G8_BAR; G8_SCHED;
.LBB0_812:
	s_add_u32 s23, s28, 0xfffe0080
	s_addc_u32 s30, s29, -1
	s_add_i32 s69, 0, 0x10000
	v_add_u32_e32 v150, s69, v162
	ds_read_b128 v[142:145], v150
	ds_read_b128 v[146:149], v150 offset:1024
	ds_read_b128 v[156:159], v150 offset:2048
	ds_read_b128 v[166:169], v150 offset:3072
	s_cmp_eq_u32 s21, 4
	s_cselect_b32 s35, s25, s30
	s_cselect_b32 s34, s24, s23
	s_cselect_b32 s31, s27, s13
	s_cselect_b32 s30, s26, s11
	v_lshl_add_u64 v[150:151], s[28:29], 0, v[138:139]
	s_add_i32 m0, s46, 0xc000
	ds_read_b128 v[190:193], v164
	ds_read_b128 v[194:197], v164 offset:1024
	ds_read_b128 v[198:201], v164 offset:2048
	ds_read_b128 v[202:205], v164 offset:3072
	ds_read_b128 v[206:209], v164 offset:4096
	ds_read_b128 v[210:213], v164 offset:5120
	ds_read_b128 v[214:217], v164 offset:6144
	ds_read_b128 v[218:221], v164 offset:7168
	global_load_lds_dwordx4 v[150:151], off
	v_lshl_add_u64 v[150:151], s[28:29], 0, v[140:141]
	s_add_i32 m0, s46, 0xe000
	s_nop 0
	global_load_lds_dwordx4 v[150:151], off
	s_waitcnt lgkmcnt(8)
	s_barrier
	s_waitcnt lgkmcnt(0)
	s_setprio 1
	s_waitcnt lgkmcnt(0)
	v_mfma_f32_16x16x32_bf16 v[128:131], v[142:145], v[190:193], v[128:131]
	v_mfma_f32_16x16x32_bf16 v[124:127], v[156:159], v[190:193], v[124:127]
	v_mfma_f32_16x16x32_bf16 v[120:123], v[142:145], v[198:201], v[120:123]
	v_mfma_f32_16x16x32_bf16 v[116:119], v[156:159], v[198:201], v[116:119]
	v_mfma_f32_16x16x32_bf16 v[112:115], v[142:145], v[206:209], v[112:115]
	v_mfma_f32_16x16x32_bf16 v[108:111], v[156:159], v[206:209], v[108:111]
	v_mfma_f32_16x16x32_bf16 v[104:107], v[142:145], v[214:217], v[104:107]
	v_mfma_f32_16x16x32_bf16 v[100:103], v[156:159], v[214:217], v[100:103]
	v_mfma_f32_16x16x32_bf16 v[128:131], v[146:149], v[194:197], v[128:131]
	v_mfma_f32_16x16x32_bf16 v[124:127], v[166:169], v[194:197], v[124:127]
	v_mfma_f32_16x16x32_bf16 v[120:123], v[146:149], v[202:205], v[120:123]
	v_mfma_f32_16x16x32_bf16 v[116:119], v[166:169], v[202:205], v[116:119]
	v_mfma_f32_16x16x32_bf16 v[112:115], v[146:149], v[210:213], v[112:115]
	v_mfma_f32_16x16x32_bf16 v[108:111], v[166:169], v[210:213], v[108:111]
	v_mfma_f32_16x16x32_bf16 v[104:107], v[146:149], v[218:221], v[104:107]
	v_mfma_f32_16x16x32_bf16 v[100:103], v[166:169], v[218:221], v[100:103]
	s_setprio 0
	s_barrier
	s_add_i32 s23, 0, 0x14000
	v_add_u32_e32 v150, s23, v162
	s_add_i32 s69, s69, s43
	ds_read_b128 v[222:225], v150
	ds_read_b128 v[226:229], v150 offset:1024
	ds_read_b128 v[230:233], v150 offset:2048
	ds_read_b128 v[234:237], v150 offset:3072
	v_lshl_add_u64 v[150:151], s[30:31], 0, v[132:133]
	s_mov_b32 m0, s69
	v_lshl_add_u64 v[160:161], s[30:31], 0, v[136:137]
	global_load_lds_dwordx4 v[150:151], off
	s_add_i32 m0, s69, 0x2000
	s_nop 0
	global_load_lds_dwordx4 v[160:161], off
	s_barrier
	s_waitcnt lgkmcnt(0)
	s_setprio 1
	s_waitcnt lgkmcnt(0)
	v_mfma_f32_16x16x32_bf16 v[96:99], v[222:225], v[190:193], v[96:99]
	v_mfma_f32_16x16x32_bf16 v[92:95], v[230:233], v[190:193], v[92:95]
	v_mfma_f32_16x16x32_bf16 v[88:91], v[222:225], v[198:201], v[88:91]
	v_mfma_f32_16x16x32_bf16 v[84:87], v[230:233], v[198:201], v[84:87]
	v_mfma_f32_16x16x32_bf16 v[80:83], v[222:225], v[206:209], v[80:83]
	v_mfma_f32_16x16x32_bf16 v[76:79], v[230:233], v[206:209], v[76:79]
	v_mfma_f32_16x16x32_bf16 v[72:75], v[222:225], v[214:217], v[72:75]
	v_mfma_f32_16x16x32_bf16 v[68:71], v[230:233], v[214:217], v[68:71]
	v_mfma_f32_16x16x32_bf16 v[96:99], v[226:229], v[194:197], v[96:99]
	v_mfma_f32_16x16x32_bf16 v[92:95], v[234:237], v[194:197], v[92:95]
	v_mfma_f32_16x16x32_bf16 v[88:91], v[226:229], v[202:205], v[88:91]
	v_mfma_f32_16x16x32_bf16 v[84:87], v[234:237], v[202:205], v[84:87]
	v_mfma_f32_16x16x32_bf16 v[80:83], v[226:229], v[210:213], v[80:83]
	v_mfma_f32_16x16x32_bf16 v[76:79], v[234:237], v[210:213], v[76:79]
	v_mfma_f32_16x16x32_bf16 v[72:75], v[226:229], v[218:221], v[72:75]
	v_mfma_f32_16x16x32_bf16 v[68:71], v[234:237], v[218:221], v[68:71]
	s_setprio 0
	s_mov_b32 m0, s46
	v_lshl_add_u64 v[238:239], s[34:35], 0, v[0:1]
	s_barrier
	ds_read_b128 v[190:193], v164 offset:16384
	ds_read_b128 v[194:197], v164 offset:17408
	ds_read_b128 v[198:201], v164 offset:18432
	ds_read_b128 v[202:205], v164 offset:19456
	ds_read_b128 v[206:209], v164 offset:20480
	ds_read_b128 v[210:213], v164 offset:21504
	ds_read_b128 v[214:217], v164 offset:22528
	ds_read_b128 v[218:221], v164 offset:23552
	global_load_lds_dwordx4 v[238:239], off
	v_lshl_add_u64 v[240:241], s[34:35], 0, v[134:135]
	s_mov_b32 m0, s47
	s_nop 0
	global_load_lds_dwordx4 v[240:241], off
	s_barrier
	s_waitcnt lgkmcnt(0)
	s_setprio 1
	s_waitcnt lgkmcnt(0)
	v_mfma_f32_16x16x32_bf16 v[64:67], v[142:145], v[190:193], v[64:67]
	v_mfma_f32_16x16x32_bf16 v[60:63], v[156:159], v[190:193], v[60:63]
	v_mfma_f32_16x16x32_bf16 v[56:59], v[142:145], v[198:201], v[56:59]
	v_mfma_f32_16x16x32_bf16 v[52:55], v[156:159], v[198:201], v[52:55]
	v_mfma_f32_16x16x32_bf16 v[48:51], v[142:145], v[206:209], v[48:51]
	v_mfma_f32_16x16x32_bf16 v[44:47], v[156:159], v[206:209], v[44:47]
	v_mfma_f32_16x16x32_bf16 v[40:43], v[142:145], v[214:217], v[40:43]
	v_mfma_f32_16x16x32_bf16 v[36:39], v[156:159], v[214:217], v[36:39]
	v_mfma_f32_16x16x32_bf16 v[64:67], v[146:149], v[194:197], v[64:67]
	v_mfma_f32_16x16x32_bf16 v[60:63], v[166:169], v[194:197], v[60:63]
	v_mfma_f32_16x16x32_bf16 v[56:59], v[146:149], v[202:205], v[56:59]
	v_mfma_f32_16x16x32_bf16 v[52:55], v[166:169], v[202:205], v[52:55]
	v_mfma_f32_16x16x32_bf16 v[48:51], v[146:149], v[210:213], v[48:51]
	v_mfma_f32_16x16x32_bf16 v[44:47], v[166:169], v[210:213], v[44:47]
	v_mfma_f32_16x16x32_bf16 v[40:43], v[146:149], v[218:221], v[40:43]
	v_mfma_f32_16x16x32_bf16 v[36:39], v[166:169], v[218:221], v[36:39]
	s_setprio 0
	s_barrier
; #define G8_STAGE(bufoff, gbase, voff) do { _Pragma("unroll") for (int _i = 0; _i < 2; ++_i) \
;     __builtin_amdgcn_global_load_lds((const unsigned*)((const char*)(gbase) + (voff)[_i]), (LAS unsigned*)(lds + (bufoff) + ldsw + _i * 8192), 16, 0, 0); } while (0)
; #define G8_LDA(dst, b, h) do { _Pragma("unroll") for (int m = 0; m < 4; ++m) _Pragma("unroll") for (int k = 0; k < 2; ++k) dst[m][k] = *(const LAS bf16x8*)(lds + G8_SA(b, h) + aoff + m * 2048 + k * 1024); } while (0)
; #define G8_LDB(dst, b, h) do { _Pragma("unroll") for (int n = 0; n < 2; ++n) _Pragma("unroll") for (int k = 0; k < 2; ++k) dst[n][k] = *(const LAS bf16x8*)(lds + G8_SB(b, h) + boff + n * 2048 + k * 1024); } while (0)
; #define G8_MMA(ai, bj, At, Bt) do { __builtin_amdgcn_s_setprio(1); _Pragma("unroll") for (int m = 0; m < 4; ++m) _Pragma("unroll") for (int n = 0; n < 2; ++n) _Pragma("unroll") for (int k = 0; k < 2; ++k) \
;     acc[ai][bj][m][n] = __builtin_amdgcn_mfma_f32_16x16x32_bf16(Bt[n][k], At[m][k], acc[ai][bj][m][n], 0, 0, 0); __builtin_amdgcn_s_setprio(0); } while (0)
; #define G8_WAIT_V(n) asm volatile("s_waitcnt vmcnt(" #n ")" ::: "memory")
; #define G8_WAIT_L(n) asm volatile("s_waitcnt lgkmcnt(" #n ")" ::: "memory")
; #define G8_BAR __builtin_amdgcn_s_barrier()
; #define G8_SCHED __builtin_amdgcn_sched_barrier(0)
; template <class Epi, class Sched>
; __device__ __forceinline__ void gemm_phase(const int wv_, LAS unsigned char* lds, const int lda, const int ldb, const int K, const Sched& S, const Epi& E) {
;     ...
;       G8_STAGE(G8_SB(0, 1), b2 + hstepB, voffB);
;       G8_WAIT_V(6); G8_BAR; G8_MMA(1, 1, At, B1); G8_BAR;
;       G8_LDB(B0, 1, 0); G8_SCHED; G8_LDA(At, 1, 0); G8_STAGE(G8_SA(0, 1), a2 + hstepA, voffA);
;       G8_WAIT_L(8); G8_BAR; G8_WAIT_L(0); G8_MMA(0, 0, At, B0); G8_BAR; G8_SCHED;
;       G8_LDB(B1, 1, 1); G8_STAGE(G8_SB(1, 0), b3, voffB);
;       G8_BAR; G8_WAIT_L(0); G8_MMA(0, 1, At, B1); G8_BAR;
;       G8_LDA(At, 1, 1); G8_STAGE(G8_SA(1, 0), a3, voffA);
;       G8_BAR; G8_WAIT_L(0); G8_MMA(1, 0, At, B0); G8_BAR; G8_SCHED;
	s_add_u32 s70, s30, 0x20000
	s_addc_u32 s71, s31, 0
	s_add_i32 s23, s23, s43
	v_lshl_add_u64 v[142:143], s[70:71], 0, v[132:133]
	s_mov_b32 m0, s23
	s_nop 0
	global_load_lds_dwordx4 v[142:143], off
	v_lshl_add_u64 v[142:143], s[70:71], 0, v[136:137]
	s_add_i32 m0, s23, 0x2000
	s_nop 0
	global_load_lds_dwordx4 v[142:143], off
	s_waitcnt vmcnt(6)
	s_barrier
	s_setprio 1
	v_mfma_f32_16x16x32_bf16 v[32:35], v[222:225], v[190:193], v[32:35]
	v_mfma_f32_16x16x32_bf16 v[28:31], v[230:233], v[190:193], v[28:31]
	v_mfma_f32_16x16x32_bf16 v[24:27], v[222:225], v[198:201], v[24:27]
	v_mfma_f32_16x16x32_bf16 v[20:23], v[230:233], v[198:201], v[20:23]
	v_mfma_f32_16x16x32_bf16 v[16:19], v[222:225], v[206:209], v[16:19]
	v_mfma_f32_16x16x32_bf16 v[12:15], v[230:233], v[206:209], v[12:15]
	v_mfma_f32_16x16x32_bf16 v[8:11], v[222:225], v[214:217], v[8:11]
	v_mfma_f32_16x16x32_bf16 v[4:7], v[230:233], v[214:217], v[4:7]
	v_mfma_f32_16x16x32_bf16 v[32:35], v[226:229], v[194:197], v[32:35]
	v_mfma_f32_16x16x32_bf16 v[28:31], v[234:237], v[194:197], v[28:31]
	v_mfma_f32_16x16x32_bf16 v[24:27], v[226:229], v[202:205], v[24:27]
	v_mfma_f32_16x16x32_bf16 v[20:23], v[234:237], v[202:205], v[20:23]
	v_mfma_f32_16x16x32_bf16 v[16:19], v[226:229], v[210:213], v[16:19]
	v_mfma_f32_16x16x32_bf16 v[12:15], v[234:237], v[210:213], v[12:15]
	v_mfma_f32_16x16x32_bf16 v[8:11], v[226:229], v[218:221], v[8:11]
	v_mfma_f32_16x16x32_bf16 v[4:7], v[234:237], v[218:221], v[4:7]
	s_setprio 0
	s_add_i32 s23, 0, 0x18000
	v_add_u32_e32 v165, s23, v162
	s_barrier
	ds_read_b128 v[142:145], v165
	ds_read_b128 v[146:149], v165 offset:1024
	ds_read_b128 v[156:159], v165 offset:2048
	ds_read_b128 v[166:169], v165 offset:3072
	s_add_u32 s34, s34, 0x20000
	s_addc_u32 s35, s35, 0
	s_mov_b32 m0, s50
	v_lshl_add_u64 v[222:223], s[34:35], 0, v[0:1]
	ds_read_b128 v[190:193], v164 offset:32768
	ds_read_b128 v[194:197], v164 offset:33792
	ds_read_b128 v[198:201], v164 offset:34816
	ds_read_b128 v[202:205], v164 offset:35840
	ds_read_b128 v[206:209], v164 offset:36864
	ds_read_b128 v[210:213], v164 offset:37888
	ds_read_b128 v[214:217], v164 offset:38912
	ds_read_b128 v[218:221], v164 offset:39936
	global_load_lds_dwordx4 v[222:223], off
	v_lshl_add_u64 v[222:223], s[34:35], 0, v[134:135]
	s_mov_b32 m0, s51
	s_nop 0
	global_load_lds_dwordx4 v[222:223], off
	s_waitcnt lgkmcnt(8)
	s_barrier
	s_waitcnt lgkmcnt(0)
	s_setprio 1
	s_waitcnt lgkmcnt(0)
	v_mfma_f32_16x16x32_bf16 v[128:131], v[142:145], v[190:193], v[128:131]
	v_mfma_f32_16x16x32_bf16 v[124:127], v[156:159], v[190:193], v[124:127]
	v_mfma_f32_16x16x32_bf16 v[120:123], v[142:145], v[198:201], v[120:123]
	v_mfma_f32_16x16x32_bf16 v[116:119], v[156:159], v[198:201], v[116:119]
	v_mfma_f32_16x16x32_bf16 v[112:115], v[142:145], v[206:209], v[112:115]
	v_mfma_f32_16x16x32_bf16 v[108:111], v[156:159], v[206:209], v[108:111]
	v_mfma_f32_16x16x32_bf16 v[104:107], v[142:145], v[214:217], v[104:107]
	v_mfma_f32_16x16x32_bf16 v[100:103], v[156:159], v[214:217], v[100:103]
	v_mfma_f32_16x16x32_bf16 v[128:131], v[146:149], v[194:197], v[128:131]
	v_mfma_f32_16x16x32_bf16 v[124:127], v[166:169], v[194:197], v[124:127]
	v_mfma_f32_16x16x32_bf16 v[120:123], v[146:149], v[202:205], v[120:123]
	v_mfma_f32_16x16x32_bf16 v[116:119], v[166:169], v[202:205], v[116:119]
	v_mfma_f32_16x16x32_bf16 v[112:115], v[146:149], v[210:213], v[112:115]
	v_mfma_f32_16x16x32_bf16 v[108:111], v[166:169], v[210:213], v[108:111]
	v_mfma_f32_16x16x32_bf16 v[104:107], v[146:149], v[218:221], v[104:107]
	v_mfma_f32_16x16x32_bf16 v[100:103], v[166:169], v[218:221], v[100:103]
	s_setprio 0
	s_barrier
	s_add_i32 s34, 0, 0x1c000
	s_add_i32 s23, s23, s43
	v_add_u32_e32 v165, s34, v162
	v_lshl_add_u64 v[150:151], v[150:151], 0, s[90:91]
	s_mov_b32 m0, s23
	ds_read_b128 v[222:225], v165
	ds_read_b128 v[226:229], v165 offset:1024
	ds_read_b128 v[230:233], v165 offset:2048
	ds_read_b128 v[234:237], v165 offset:3072
	global_load_lds_dwordx4 v[150:151], off
	v_lshl_add_u64 v[150:151], v[160:161], 0, s[90:91]
	s_add_i32 m0, s23, 0x2000
	s_nop 0
	global_load_lds_dwordx4 v[150:151], off
	s_barrier
	s_waitcnt lgkmcnt(0)
	s_setprio 1
	s_waitcnt lgkmcnt(0)
	v_mfma_f32_16x16x32_bf16 v[96:99], v[222:225], v[190:193], v[96:99]
	v_mfma_f32_16x16x32_bf16 v[92:95], v[230:233], v[190:193], v[92:95]
	v_mfma_f32_16x16x32_bf16 v[88:91], v[222:225], v[198:201], v[88:91]
	v_mfma_f32_16x16x32_bf16 v[84:87], v[230:233], v[198:201], v[84:87]
	v_mfma_f32_16x16x32_bf16 v[80:83], v[222:225], v[206:209], v[80:83]
	v_mfma_f32_16x16x32_bf16 v[76:79], v[230:233], v[206:209], v[76:79]
	v_mfma_f32_16x16x32_bf16 v[72:75], v[222:225], v[214:217], v[72:75]
	v_mfma_f32_16x16x32_bf16 v[68:71], v[230:233], v[214:217], v[68:71]
	v_mfma_f32_16x16x32_bf16 v[96:99], v[226:229], v[194:197], v[96:99]
	v_mfma_f32_16x16x32_bf16 v[92:95], v[234:237], v[194:197], v[92:95]
	v_mfma_f32_16x16x32_bf16 v[88:91], v[226:229], v[202:205], v[88:91]
	v_mfma_f32_16x16x32_bf16 v[84:87], v[234:237], v[202:205], v[84:87]
	v_mfma_f32_16x16x32_bf16 v[80:83], v[226:229], v[210:213], v[80:83]
	v_mfma_f32_16x16x32_bf16 v[76:79], v[234:237], v[210:213], v[76:79]
	v_mfma_f32_16x16x32_bf16 v[72:75], v[226:229], v[218:221], v[72:75]
	v_mfma_f32_16x16x32_bf16 v[68:71], v[234:237], v[218:221], v[68:71]
	s_setprio 0
	s_mov_b32 m0, s56
	v_lshl_add_u64 v[150:151], v[238:239], 0, s[90:91]
	s_barrier
	ds_read_b128 v[190:193], v164 offset:49152
	ds_read_b128 v[194:197], v164 offset:50176
	ds_read_b128 v[198:201], v164 offset:51200
	ds_read_b128 v[202:205], v164 offset:52224
	ds_read_b128 v[206:209], v164 offset:53248
	ds_read_b128 v[210:213], v164 offset:54272
	ds_read_b128 v[214:217], v164 offset:55296
	ds_read_b128 v[218:221], v164 offset:56320
	global_load_lds_dwordx4 v[150:151], off
	v_lshl_add_u64 v[150:151], v[240:241], 0, s[90:91]
	s_mov_b32 m0, s57
	s_nop 0
	global_load_lds_dwordx4 v[150:151], off
	s_barrier
; __device__ __forceinline__ float lo16(unsigned u) { return __uint_as_float(u << 16); }
; __device__ __forceinline__ float hi16(unsigned u) { return __uint_as_float(u & 0xffff0000u); }
; #define G8_STAGE(bufoff, gbase, voff) do { _Pragma("unroll") for (int _i = 0; _i < 2; ++_i) \
;     __builtin_amdgcn_global_load_lds((const unsigned*)((const char*)(gbase) + (voff)[_i]), (LAS unsigned*)(lds + (bufoff) + ldsw + _i * 8192), 16, 0, 0); } while (0)
; #define G8_MMA(ai, bj, At, Bt) do { __builtin_amdgcn_s_setprio(1); _Pragma("unroll") for (int m = 0; m < 4; ++m) _Pragma("unroll") for (int n = 0; n < 2; ++n) _Pragma("unroll") for (int k = 0; k < 2; ++k) \
;     acc[ai][bj][m][n] = __builtin_amdgcn_mfma_f32_16x16x32_bf16(Bt[n][k], At[m][k], acc[ai][bj][m][n], 0, 0, 0); __builtin_amdgcn_s_setprio(0); } while (0)
; #define G8_WAIT_V(n) asm volatile("s_waitcnt vmcnt(" #n ")" ::: "memory")
; #define G8_WAIT_L(n) asm volatile("s_waitcnt lgkmcnt(" #n ")" ::: "memory")
; #define G8_BAR __builtin_amdgcn_s_barrier()
; #define G8_SCHED __builtin_amdgcn_sched_barrier(0)
; template <class Epi, class Sched>
; __device__ __forceinline__ void gemm_phase(const int wv_, LAS unsigned char* lds, const int lda, const int ldb, const int K, const Sched& S, const Epi& E) {
;     ...
;       G8_BAR; G8_WAIT_L(0); G8_MMA(1, 0, At, B0); G8_BAR; G8_SCHED;
;       G8_STAGE(G8_SB(1, 1), b3 + hstepB, voffB);
;       G8_WAIT_V(6); G8_BAR; G8_MMA(1, 1, At, B1); G8_BAR;
;   __device__ __forceinline__ bool operator()(f32x4 (&acc)[2][2][4][2], const Unit& u, int wr, int wc, int fr, int fq) const {
;     ...
;           const bf16_t* sp = pg + row * 8192 + (size_t)j * 2048 + col0 + bj * HALF;
;           const u32x4 sc = *(const u32x4*)sp;
;           float f[8] = {lo16(sc.x), hi16(sc.x), lo16(sc.y), hi16(sc.y), lo16(sc.z), hi16(sc.z), lo16(sc.w), hi16(sc.w)};
;           if (j < 3) { const u32x4 sn = *(const u32x4*)(sp + 2048);
;             float g[8] = {lo16(sn.x), hi16(sn.x), lo16(sn.y), hi16(sn.y), lo16(sn.z), hi16(sn.z), lo16(sn.w), hi16(sn.w)};
; #pragma unroll
;             for (int e = 0; e < 8; ++e) f[e] = f[e] * __builtin_amdgcn_rcpf(fmaxf(g[e], 1e-30f)); }
;           f32x4 v0 = acc[ai][bj][m][0], v1 = acc[ai][bj][m][1];
; #pragma unroll
;           for (int e = 0; e < 4; ++e) { v0[e] *= f[e]; v1[e] *= f[4 + e]; }
	s_waitcnt lgkmcnt(0)
	s_setprio 1
	s_waitcnt lgkmcnt(0)
	v_mfma_f32_16x16x32_bf16 v[64:67], v[142:145], v[190:193], v[64:67]
	v_mfma_f32_16x16x32_bf16 v[60:63], v[156:159], v[190:193], v[60:63]
	v_mfma_f32_16x16x32_bf16 v[56:59], v[142:145], v[198:201], v[56:59]
	v_mfma_f32_16x16x32_bf16 v[52:55], v[156:159], v[198:201], v[52:55]
	v_mfma_f32_16x16x32_bf16 v[48:51], v[142:145], v[206:209], v[48:51]
	v_mfma_f32_16x16x32_bf16 v[44:47], v[156:159], v[206:209], v[44:47]
	v_mfma_f32_16x16x32_bf16 v[40:43], v[142:145], v[214:217], v[40:43]
	v_mfma_f32_16x16x32_bf16 v[36:39], v[156:159], v[214:217], v[36:39]
	v_mfma_f32_16x16x32_bf16 v[64:67], v[146:149], v[194:197], v[64:67]
	v_mfma_f32_16x16x32_bf16 v[60:63], v[166:169], v[194:197], v[60:63]
	v_mfma_f32_16x16x32_bf16 v[56:59], v[146:149], v[202:205], v[56:59]
	v_mfma_f32_16x16x32_bf16 v[52:55], v[166:169], v[202:205], v[52:55]
	v_mfma_f32_16x16x32_bf16 v[48:51], v[146:149], v[210:213], v[48:51]
	v_mfma_f32_16x16x32_bf16 v[44:47], v[166:169], v[210:213], v[44:47]
	v_mfma_f32_16x16x32_bf16 v[40:43], v[146:149], v[218:221], v[40:43]
	v_mfma_f32_16x16x32_bf16 v[36:39], v[166:169], v[218:221], v[36:39]
	s_setprio 0
	s_barrier
	s_add_u32 s30, s30, 0x20080
	s_addc_u32 s31, s31, 0
	s_add_i32 s23, s34, s43
	v_lshl_add_u64 v[142:143], s[30:31], 0, v[132:133]
	s_mov_b32 m0, s23
	s_nop 0
	global_load_lds_dwordx4 v[142:143], off
	v_lshl_add_u64 v[142:143], s[30:31], 0, v[136:137]
	s_add_i32 m0, s23, 0x2000
	s_nop 0
	global_load_lds_dwordx4 v[142:143], off
	s_waitcnt vmcnt(6)
	s_barrier
	s_setprio 1
	v_mfma_f32_16x16x32_bf16 v[32:35], v[222:225], v[190:193], v[32:35]
	v_mfma_f32_16x16x32_bf16 v[28:31], v[230:233], v[190:193], v[28:31]
	v_mfma_f32_16x16x32_bf16 v[24:27], v[222:225], v[198:201], v[24:27]
	v_mfma_f32_16x16x32_bf16 v[20:23], v[230:233], v[198:201], v[20:23]
	v_mfma_f32_16x16x32_bf16 v[16:19], v[222:225], v[206:209], v[16:19]
	v_mfma_f32_16x16x32_bf16 v[12:15], v[230:233], v[206:209], v[12:15]
	v_mfma_f32_16x16x32_bf16 v[8:11], v[222:225], v[214:217], v[8:11]
	v_mfma_f32_16x16x32_bf16 v[4:7], v[230:233], v[214:217], v[4:7]
	v_mfma_f32_16x16x32_bf16 v[32:35], v[226:229], v[194:197], v[32:35]
	v_mfma_f32_16x16x32_bf16 v[28:31], v[234:237], v[194:197], v[28:31]
	v_mfma_f32_16x16x32_bf16 v[24:27], v[226:229], v[202:205], v[24:27]
	v_mfma_f32_16x16x32_bf16 v[20:23], v[234:237], v[202:205], v[20:23]
	v_mfma_f32_16x16x32_bf16 v[16:19], v[226:229], v[210:213], v[16:19]
	v_mfma_f32_16x16x32_bf16 v[12:15], v[234:237], v[210:213], v[12:15]
	v_mfma_f32_16x16x32_bf16 v[8:11], v[226:229], v[218:221], v[8:11]
	v_mfma_f32_16x16x32_bf16 v[4:7], v[234:237], v[218:221], v[4:7]
	s_setprio 0
	s_add_i32 s21, s21, 2
	s_add_u32 s28, s28, 0x100
	s_addc_u32 s29, s29, 0
	s_add_u32 s11, s11, 0x100
	s_addc_u32 s13, s13, 0
	s_cmp_gt_u32 s21, 5
	s_barrier
	s_cbranch_scc0 .LBB0_812
	s_lshl_b32 s11, s12, 22
	s_lshl_b32 s13, s10, 12
	s_add_u32 s30, s16, s11
	s_addc_u32 s31, s17, 0
	s_add_u32 s30, s30, s13
	s_addc_u32 s31, s31, 0
	s_lshl_b32 s13, s68, 9
	s_add_u32 s30, s30, s13
	s_addc_u32 s31, s31, 0
	v_lshlrev_b32_e32 v165, 1, v163
	v_lshl_add_u32 v160, v3, 14, v165
	v_mov_b32_e32 v161, 0
	v_lshl_add_u64 v[160:161], v[160:161], 0, s[30:31]
	s_mov_b32 s28, 0x40000
	s_mov_b32 s29, 0
	s_cmp_eq_u32 s10, 3
	s_cbranch_scc1 .Lg2e_eq3
	s_mov_b64 s[34:35], 0x1000
	v_lshl_add_u64 v[150:151], v[160:161], 0, s[34:35]
	global_load_dwordx4 v[190:193], v[160:161], off
	global_load_dwordx4 v[194:197], v[150:151], off
	global_load_dwordx4 v[198:201], v[160:161], off offset:256
	global_load_dwordx4 v[202:205], v[150:151], off offset:256
	v_lshl_add_u64 v[160:161], v[160:161], 0, s[28:29]
	v_lshl_add_u64 v[150:151], v[150:151], 0, s[28:29]
	global_load_dwordx4 v[206:209], v[160:161], off
	global_load_dwordx4 v[210:213], v[150:151], off
	global_load_dwordx4 v[214:217], v[160:161], off offset:256
	global_load_dwordx4 v[218:221], v[150:151], off offset:256
	v_lshl_add_u64 v[160:161], v[160:161], 0, s[28:29]
	v_lshl_add_u64 v[150:151], v[150:151], 0, s[28:29]
	global_load_dwordx4 v[222:225], v[160:161], off
	global_load_dwordx4 v[226:229], v[150:151], off
	global_load_dwordx4 v[230:233], v[160:161], off offset:256
	global_load_dwordx4 v[234:237], v[150:151], off offset:256
	v_lshl_add_u64 v[160:161], v[160:161], 0, s[28:29]
	v_lshl_add_u64 v[150:151], v[150:151], 0, s[28:29]
	global_load_dwordx4 v[238:241], v[160:161], off
	global_load_dwordx4 v[142:145], v[150:151], off
	global_load_dwordx4 v[146:149], v[160:161], off offset:256
	global_load_dwordx4 v[156:159], v[150:151], off offset:256
	s_mov_b32 s28, 0x140000
	v_lshl_add_u64 v[160:161], v[160:161], 0, s[28:29]
	s_mov_b32 s28, 0x40000
	s_mov_b32 s28, 0x140000
	v_lshl_add_u64 v[150:151], v[150:151], 0, s[28:29]
	s_mov_b32 s28, 0x40000
	s_waitcnt vmcnt(14)
	v_lshlrev_b32_e32 v168, 16, v194
	v_and_b32_e32 v169, 0xffff0000, v194
	v_max_f32_e32 v168, 0xda24260, v168
	v_max_f32_e32 v169, 0xda24260, v169
	v_rcp_f32_e32 v168, v168
	v_rcp_f32_e32 v169, v169
	v_lshlrev_b32_e32 v166, 16, v190
	v_and_b32_e32 v167, 0xffff0000, v190
	v_pk_mul_f32 v[166:167], v[168:169], v[166:167]
	v_pk_mul_f32 v[128:129], v[128:129], v[166:167]
	v_lshlrev_b32_e32 v168, 16, v195
	v_and_b32_e32 v169, 0xffff0000, v195
	v_max_f32_e32 v168, 0xda24260, v168
	v_max_f32_e32 v169, 0xda24260, v169
	v_rcp_f32_e32 v168, v168
	v_rcp_f32_e32 v169, v169
	v_lshlrev_b32_e32 v166, 16, v191
	v_and_b32_e32 v167, 0xffff0000, v191
	v_pk_mul_f32 v[166:167], v[168:169], v[166:167]
	v_pk_mul_f32 v[130:131], v[130:131], v[166:167]
	v_lshlrev_b32_e32 v168, 16, v196
	v_and_b32_e32 v169, 0xffff0000, v196
	v_max_f32_e32 v168, 0xda24260, v168
	v_max_f32_e32 v169, 0xda24260, v169
	v_rcp_f32_e32 v168, v168
	v_rcp_f32_e32 v169, v169
	v_lshlrev_b32_e32 v166, 16, v192
	v_and_b32_e32 v167, 0xffff0000, v192
	v_pk_mul_f32 v[166:167], v[168:169], v[166:167]
	v_pk_mul_f32 v[124:125], v[124:125], v[166:167]
	v_lshlrev_b32_e32 v168, 16, v197
	v_and_b32_e32 v169, 0xffff0000, v197
	v_max_f32_e32 v168, 0xda24260, v168
	v_max_f32_e32 v169, 0xda24260, v169
	v_rcp_f32_e32 v168, v168
	v_rcp_f32_e32 v169, v169
	v_lshlrev_b32_e32 v166, 16, v193
	v_and_b32_e32 v167, 0xffff0000, v193
	v_pk_mul_f32 v[166:167], v[168:169], v[166:167]
	v_pk_mul_f32 v[126:127], v[126:127], v[166:167]
	global_load_dwordx4 v[190:193], v[160:161], off
	global_load_dwordx4 v[194:197], v[150:151], off
	s_waitcnt vmcnt(14)
; __device__ __forceinline__ float lo16(unsigned u) { return __uint_as_float(u << 16); }
; __device__ __forceinline__ float hi16(unsigned u) { return __uint_as_float(u & 0xffff0000u); }
;   __device__ __forceinline__ bool operator()(f32x4 (&acc)[2][2][4][2], const Unit& u, int wr, int wc, int fr, int fq) const {
;     ...
;           const bf16_t* sp = pg + row * 8192 + (size_t)j * 2048 + col0 + bj * HALF;
;           const u32x4 sc = *(const u32x4*)sp;
;           float f[8] = {lo16(sc.x), hi16(sc.x), lo16(sc.y), hi16(sc.y), lo16(sc.z), hi16(sc.z), lo16(sc.w), hi16(sc.w)};
;           if (j < 3) { const u32x4 sn = *(const u32x4*)(sp + 2048);
;             float g[8] = {lo16(sn.x), hi16(sn.x), lo16(sn.y), hi16(sn.y), lo16(sn.z), hi16(sn.z), lo16(sn.w), hi16(sn.w)};
; #pragma unroll
;             for (int e = 0; e < 8; ++e) f[e] = f[e] * __builtin_amdgcn_rcpf(fmaxf(g[e], 1e-30f)); }
;           f32x4 v0 = acc[ai][bj][m][0], v1 = acc[ai][bj][m][1];
; #pragma unroll
;           for (int e = 0; e < 4; ++e) { v0[e] *= f[e]; v1[e] *= f[4 + e]; }
;           acc[ai][bj][m][0] = v0; acc[ai][bj][m][1] = v1;
	v_lshlrev_b32_e32 v168, 16, v202
	v_and_b32_e32 v169, 0xffff0000, v202
	v_max_f32_e32 v168, 0xda24260, v168
	v_max_f32_e32 v169, 0xda24260, v169
	v_rcp_f32_e32 v168, v168
	v_rcp_f32_e32 v169, v169
	v_lshlrev_b32_e32 v166, 16, v198
	v_and_b32_e32 v167, 0xffff0000, v198
	v_pk_mul_f32 v[166:167], v[168:169], v[166:167]
	v_pk_mul_f32 v[96:97], v[96:97], v[166:167]
	v_lshlrev_b32_e32 v168, 16, v203
	v_and_b32_e32 v169, 0xffff0000, v203
	v_max_f32_e32 v168, 0xda24260, v168
	v_max_f32_e32 v169, 0xda24260, v169
	v_rcp_f32_e32 v168, v168
	v_rcp_f32_e32 v169, v169
	v_lshlrev_b32_e32 v166, 16, v199
	v_and_b32_e32 v167, 0xffff0000, v199
	v_pk_mul_f32 v[166:167], v[168:169], v[166:167]
	v_pk_mul_f32 v[98:99], v[98:99], v[166:167]
	v_lshlrev_b32_e32 v168, 16, v204
	v_and_b32_e32 v169, 0xffff0000, v204
	v_max_f32_e32 v168, 0xda24260, v168
	v_max_f32_e32 v169, 0xda24260, v169
	v_rcp_f32_e32 v168, v168
	v_rcp_f32_e32 v169, v169
	v_lshlrev_b32_e32 v166, 16, v200
	v_and_b32_e32 v167, 0xffff0000, v200
	v_pk_mul_f32 v[166:167], v[168:169], v[166:167]
	v_pk_mul_f32 v[92:93], v[92:93], v[166:167]
	v_lshlrev_b32_e32 v168, 16, v205
	v_and_b32_e32 v169, 0xffff0000, v205
	v_max_f32_e32 v168, 0xda24260, v168
	v_max_f32_e32 v169, 0xda24260, v169
	v_rcp_f32_e32 v168, v168
	v_rcp_f32_e32 v169, v169
	v_lshlrev_b32_e32 v166, 16, v201
	v_and_b32_e32 v167, 0xffff0000, v201
	v_pk_mul_f32 v[166:167], v[168:169], v[166:167]
	v_pk_mul_f32 v[94:95], v[94:95], v[166:167]
	global_load_dwordx4 v[198:201], v[160:161], off offset:256
	global_load_dwordx4 v[202:205], v[150:151], off offset:256
	v_lshl_add_u64 v[160:161], v[160:161], 0, s[28:29]
	v_lshl_add_u64 v[150:151], v[150:151], 0, s[28:29]
	s_waitcnt vmcnt(14)
	v_lshlrev_b32_e32 v168, 16, v210
	v_and_b32_e32 v169, 0xffff0000, v210
	v_max_f32_e32 v168, 0xda24260, v168
	v_max_f32_e32 v169, 0xda24260, v169
	v_rcp_f32_e32 v168, v168
	v_rcp_f32_e32 v169, v169
	v_lshlrev_b32_e32 v166, 16, v206
	v_and_b32_e32 v167, 0xffff0000, v206
	v_pk_mul_f32 v[166:167], v[168:169], v[166:167]
	v_pk_mul_f32 v[120:121], v[120:121], v[166:167]
	v_lshlrev_b32_e32 v168, 16, v211
	v_and_b32_e32 v169, 0xffff0000, v211
	v_max_f32_e32 v168, 0xda24260, v168
	v_max_f32_e32 v169, 0xda24260, v169
	v_rcp_f32_e32 v168, v168
	v_rcp_f32_e32 v169, v169
	v_lshlrev_b32_e32 v166, 16, v207
	v_and_b32_e32 v167, 0xffff0000, v207
	v_pk_mul_f32 v[166:167], v[168:169], v[166:167]
	v_pk_mul_f32 v[122:123], v[122:123], v[166:167]
	v_lshlrev_b32_e32 v168, 16, v212
	v_and_b32_e32 v169, 0xffff0000, v212
	v_max_f32_e32 v168, 0xda24260, v168
	v_max_f32_e32 v169, 0xda24260, v169
	v_rcp_f32_e32 v168, v168
	v_rcp_f32_e32 v169, v169
	v_lshlrev_b32_e32 v166, 16, v208
	v_and_b32_e32 v167, 0xffff0000, v208
	v_pk_mul_f32 v[166:167], v[168:169], v[166:167]
	v_pk_mul_f32 v[116:117], v[116:117], v[166:167]
	v_lshlrev_b32_e32 v168, 16, v213
	v_and_b32_e32 v169, 0xffff0000, v213
	v_max_f32_e32 v168, 0xda24260, v168
	v_max_f32_e32 v169, 0xda24260, v169
	v_rcp_f32_e32 v168, v168
	v_rcp_f32_e32 v169, v169
	v_lshlrev_b32_e32 v166, 16, v209
	v_and_b32_e32 v167, 0xffff0000, v209
	v_pk_mul_f32 v[166:167], v[168:169], v[166:167]
	v_pk_mul_f32 v[118:119], v[118:119], v[166:167]
	global_load_dwordx4 v[206:209], v[160:161], off
	global_load_dwordx4 v[210:213], v[150:151], off
	s_waitcnt vmcnt(14)
	v_lshlrev_b32_e32 v168, 16, v218
	v_and_b32_e32 v169, 0xffff0000, v218
	v_max_f32_e32 v168, 0xda24260, v168
	v_max_f32_e32 v169, 0xda24260, v169
	v_rcp_f32_e32 v168, v168
	v_rcp_f32_e32 v169, v169
	v_lshlrev_b32_e32 v166, 16, v214
	v_and_b32_e32 v167, 0xffff0000, v214
	v_pk_mul_f32 v[166:167], v[168:169], v[166:167]
	v_pk_mul_f32 v[88:89], v[88:89], v[166:167]
	v_lshlrev_b32_e32 v168, 16, v219
	v_and_b32_e32 v169, 0xffff0000, v219
	v_max_f32_e32 v168, 0xda24260, v168
	v_max_f32_e32 v169, 0xda24260, v169
	v_rcp_f32_e32 v168, v168
	v_rcp_f32_e32 v169, v169
	v_lshlrev_b32_e32 v166, 16, v215
	v_and_b32_e32 v167, 0xffff0000, v215
	v_pk_mul_f32 v[166:167], v[168:169], v[166:167]
	v_pk_mul_f32 v[90:91], v[90:91], v[166:167]
	v_lshlrev_b32_e32 v168, 16, v220
	v_and_b32_e32 v169, 0xffff0000, v220
	v_max_f32_e32 v168, 0xda24260, v168
	v_max_f32_e32 v169, 0xda24260, v169
	v_rcp_f32_e32 v168, v168
	v_rcp_f32_e32 v169, v169
	v_lshlrev_b32_e32 v166, 16, v216
	v_and_b32_e32 v167, 0xffff0000, v216
	v_pk_mul_f32 v[166:167], v[168:169], v[166:167]
	v_pk_mul_f32 v[84:85], v[84:85], v[166:167]
	v_lshlrev_b32_e32 v168, 16, v221
	v_and_b32_e32 v169, 0xffff0000, v221
	v_max_f32_e32 v168, 0xda24260, v168
	v_max_f32_e32 v169, 0xda24260, v169
	v_rcp_f32_e32 v168, v168
	v_rcp_f32_e32 v169, v169
	v_lshlrev_b32_e32 v166, 16, v217
	v_and_b32_e32 v167, 0xffff0000, v217
	v_pk_mul_f32 v[166:167], v[168:169], v[166:167]
	v_pk_mul_f32 v[86:87], v[86:87], v[166:167]
	global_load_dwordx4 v[214:217], v[160:161], off offset:256
	global_load_dwordx4 v[218:221], v[150:151], off offset:256
	v_lshl_add_u64 v[160:161], v[160:161], 0, s[28:29]
	v_lshl_add_u64 v[150:151], v[150:151], 0, s[28:29]
	s_waitcnt vmcnt(14)
; __device__ __forceinline__ float lo16(unsigned u) { return __uint_as_float(u << 16); }
; __device__ __forceinline__ float hi16(unsigned u) { return __uint_as_float(u & 0xffff0000u); }
;   __device__ __forceinline__ bool operator()(f32x4 (&acc)[2][2][4][2], const Unit& u, int wr, int wc, int fr, int fq) const {
;     ...
;           const bf16_t* sp = pg + row * 8192 + (size_t)j * 2048 + col0 + bj * HALF;
;           const u32x4 sc = *(const u32x4*)sp;
;           float f[8] = {lo16(sc.x), hi16(sc.x), lo16(sc.y), hi16(sc.y), lo16(sc.z), hi16(sc.z), lo16(sc.w), hi16(sc.w)};
;           if (j < 3) { const u32x4 sn = *(const u32x4*)(sp + 2048);
;             float g[8] = {lo16(sn.x), hi16(sn.x), lo16(sn.y), hi16(sn.y), lo16(sn.z), hi16(sn.z), lo16(sn.w), hi16(sn.w)};
; #pragma unroll
;             for (int e = 0; e < 8; ++e) f[e] = f[e] * __builtin_amdgcn_rcpf(fmaxf(g[e], 1e-30f)); }
;           f32x4 v0 = acc[ai][bj][m][0], v1 = acc[ai][bj][m][1];
; #pragma unroll
;           for (int e = 0; e < 4; ++e) { v0[e] *= f[e]; v1[e] *= f[4 + e]; }
;           acc[ai][bj][m][0] = v0; acc[ai][bj][m][1] = v1;
	v_lshlrev_b32_e32 v168, 16, v226
	v_and_b32_e32 v169, 0xffff0000, v226
	v_max_f32_e32 v168, 0xda24260, v168
	v_max_f32_e32 v169, 0xda24260, v169
	v_rcp_f32_e32 v168, v168
	v_rcp_f32_e32 v169, v169
	v_lshlrev_b32_e32 v166, 16, v222
	v_and_b32_e32 v167, 0xffff0000, v222
	v_pk_mul_f32 v[166:167], v[168:169], v[166:167]
	v_pk_mul_f32 v[112:113], v[112:113], v[166:167]
	v_lshlrev_b32_e32 v168, 16, v227
	v_and_b32_e32 v169, 0xffff0000, v227
	v_max_f32_e32 v168, 0xda24260, v168
	v_max_f32_e32 v169, 0xda24260, v169
	v_rcp_f32_e32 v168, v168
	v_rcp_f32_e32 v169, v169
	v_lshlrev_b32_e32 v166, 16, v223
	v_and_b32_e32 v167, 0xffff0000, v223
	v_pk_mul_f32 v[166:167], v[168:169], v[166:167]
	v_pk_mul_f32 v[114:115], v[114:115], v[166:167]
	v_lshlrev_b32_e32 v168, 16, v228
	v_and_b32_e32 v169, 0xffff0000, v228
	v_max_f32_e32 v168, 0xda24260, v168
	v_max_f32_e32 v169, 0xda24260, v169
	v_rcp_f32_e32 v168, v168
	v_rcp_f32_e32 v169, v169
	v_lshlrev_b32_e32 v166, 16, v224
	v_and_b32_e32 v167, 0xffff0000, v224
	v_pk_mul_f32 v[166:167], v[168:169], v[166:167]
	v_pk_mul_f32 v[108:109], v[108:109], v[166:167]
	v_lshlrev_b32_e32 v168, 16, v229
	v_and_b32_e32 v169, 0xffff0000, v229
	v_max_f32_e32 v168, 0xda24260, v168
	v_max_f32_e32 v169, 0xda24260, v169
	v_rcp_f32_e32 v168, v168
	v_rcp_f32_e32 v169, v169
	v_lshlrev_b32_e32 v166, 16, v225
	v_and_b32_e32 v167, 0xffff0000, v225
	v_pk_mul_f32 v[166:167], v[168:169], v[166:167]
	v_pk_mul_f32 v[110:111], v[110:111], v[166:167]
	global_load_dwordx4 v[222:225], v[160:161], off
	global_load_dwordx4 v[226:229], v[150:151], off
	s_waitcnt vmcnt(14)
	v_lshlrev_b32_e32 v168, 16, v234
	v_and_b32_e32 v169, 0xffff0000, v234
	v_max_f32_e32 v168, 0xda24260, v168
	v_max_f32_e32 v169, 0xda24260, v169
	v_rcp_f32_e32 v168, v168
	v_rcp_f32_e32 v169, v169
	v_lshlrev_b32_e32 v166, 16, v230
	v_and_b32_e32 v167, 0xffff0000, v230
	v_pk_mul_f32 v[166:167], v[168:169], v[166:167]
	v_pk_mul_f32 v[80:81], v[80:81], v[166:167]
	v_lshlrev_b32_e32 v168, 16, v235
	v_and_b32_e32 v169, 0xffff0000, v235
	v_max_f32_e32 v168, 0xda24260, v168
	v_max_f32_e32 v169, 0xda24260, v169
	v_rcp_f32_e32 v168, v168
	v_rcp_f32_e32 v169, v169
	v_lshlrev_b32_e32 v166, 16, v231
	v_and_b32_e32 v167, 0xffff0000, v231
	v_pk_mul_f32 v[166:167], v[168:169], v[166:167]
	v_pk_mul_f32 v[82:83], v[82:83], v[166:167]
	v_lshlrev_b32_e32 v168, 16, v236
	v_and_b32_e32 v169, 0xffff0000, v236
	v_max_f32_e32 v168, 0xda24260, v168
	v_max_f32_e32 v169, 0xda24260, v169
	v_rcp_f32_e32 v168, v168
	v_rcp_f32_e32 v169, v169
	v_lshlrev_b32_e32 v166, 16, v232
	v_and_b32_e32 v167, 0xffff0000, v232
	v_pk_mul_f32 v[166:167], v[168:169], v[166:167]
	v_pk_mul_f32 v[76:77], v[76:77], v[166:167]
	v_lshlrev_b32_e32 v168, 16, v237
	v_and_b32_e32 v169, 0xffff0000, v237
	v_max_f32_e32 v168, 0xda24260, v168
	v_max_f32_e32 v169, 0xda24260, v169
	v_rcp_f32_e32 v168, v168
	v_rcp_f32_e32 v169, v169
	v_lshlrev_b32_e32 v166, 16, v233
	v_and_b32_e32 v167, 0xffff0000, v233
	v_pk_mul_f32 v[166:167], v[168:169], v[166:167]
	v_pk_mul_f32 v[78:79], v[78:79], v[166:167]
	global_load_dwordx4 v[230:233], v[160:161], off offset:256
	global_load_dwordx4 v[234:237], v[150:151], off offset:256
	v_lshl_add_u64 v[160:161], v[160:161], 0, s[28:29]
	v_lshl_add_u64 v[150:151], v[150:151], 0, s[28:29]
	s_waitcnt vmcnt(14)
	v_lshlrev_b32_e32 v168, 16, v142
	v_and_b32_e32 v169, 0xffff0000, v142
	v_max_f32_e32 v168, 0xda24260, v168
	v_max_f32_e32 v169, 0xda24260, v169
	v_rcp_f32_e32 v168, v168
	v_rcp_f32_e32 v169, v169
	v_lshlrev_b32_e32 v166, 16, v238
	v_and_b32_e32 v167, 0xffff0000, v238
	v_pk_mul_f32 v[166:167], v[168:169], v[166:167]
	v_pk_mul_f32 v[104:105], v[104:105], v[166:167]
	v_lshlrev_b32_e32 v168, 16, v143
	v_and_b32_e32 v169, 0xffff0000, v143
	v_max_f32_e32 v168, 0xda24260, v168
	v_max_f32_e32 v169, 0xda24260, v169
	v_rcp_f32_e32 v168, v168
	v_rcp_f32_e32 v169, v169
	v_lshlrev_b32_e32 v166, 16, v239
	v_and_b32_e32 v167, 0xffff0000, v239
	v_pk_mul_f32 v[166:167], v[168:169], v[166:167]
	v_pk_mul_f32 v[106:107], v[106:107], v[166:167]
	v_lshlrev_b32_e32 v168, 16, v144
	v_and_b32_e32 v169, 0xffff0000, v144
	v_max_f32_e32 v168, 0xda24260, v168
	v_max_f32_e32 v169, 0xda24260, v169
	v_rcp_f32_e32 v168, v168
	v_rcp_f32_e32 v169, v169
	v_lshlrev_b32_e32 v166, 16, v240
	v_and_b32_e32 v167, 0xffff0000, v240
	v_pk_mul_f32 v[166:167], v[168:169], v[166:167]
	v_pk_mul_f32 v[100:101], v[100:101], v[166:167]
	v_lshlrev_b32_e32 v168, 16, v145
	v_and_b32_e32 v169, 0xffff0000, v145
	v_max_f32_e32 v168, 0xda24260, v168
	v_max_f32_e32 v169, 0xda24260, v169
	v_rcp_f32_e32 v168, v168
	v_rcp_f32_e32 v169, v169
	v_lshlrev_b32_e32 v166, 16, v241
	v_and_b32_e32 v167, 0xffff0000, v241
	v_pk_mul_f32 v[166:167], v[168:169], v[166:167]
	v_pk_mul_f32 v[102:103], v[102:103], v[166:167]
	global_load_dwordx4 v[238:241], v[160:161], off
	global_load_dwordx4 v[142:145], v[150:151], off
	s_waitcnt vmcnt(14)
; __device__ __forceinline__ float lo16(unsigned u) { return __uint_as_float(u << 16); }
; __device__ __forceinline__ float hi16(unsigned u) { return __uint_as_float(u & 0xffff0000u); }
;   __device__ __forceinline__ bool operator()(f32x4 (&acc)[2][2][4][2], const Unit& u, int wr, int wc, int fr, int fq) const {
;     ...
;           const bf16_t* sp = pg + row * 8192 + (size_t)j * 2048 + col0 + bj * HALF;
;           const u32x4 sc = *(const u32x4*)sp;
;           float f[8] = {lo16(sc.x), hi16(sc.x), lo16(sc.y), hi16(sc.y), lo16(sc.z), hi16(sc.z), lo16(sc.w), hi16(sc.w)};
;           if (j < 3) { const u32x4 sn = *(const u32x4*)(sp + 2048);
;             float g[8] = {lo16(sn.x), hi16(sn.x), lo16(sn.y), hi16(sn.y), lo16(sn.z), hi16(sn.z), lo16(sn.w), hi16(sn.w)};
; #pragma unroll
;             for (int e = 0; e < 8; ++e) f[e] = f[e] * __builtin_amdgcn_rcpf(fmaxf(g[e], 1e-30f)); }
;           f32x4 v0 = acc[ai][bj][m][0], v1 = acc[ai][bj][m][1];
; #pragma unroll
;           for (int e = 0; e < 4; ++e) { v0[e] *= f[e]; v1[e] *= f[4 + e]; }
;           acc[ai][bj][m][0] = v0; acc[ai][bj][m][1] = v1;
	v_lshlrev_b32_e32 v168, 16, v156
	v_and_b32_e32 v169, 0xffff0000, v156
	v_max_f32_e32 v168, 0xda24260, v168
	v_max_f32_e32 v169, 0xda24260, v169
	v_rcp_f32_e32 v168, v168
	v_rcp_f32_e32 v169, v169
	v_lshlrev_b32_e32 v166, 16, v146
	v_and_b32_e32 v167, 0xffff0000, v146
	v_pk_mul_f32 v[166:167], v[168:169], v[166:167]
	v_pk_mul_f32 v[72:73], v[72:73], v[166:167]
	v_lshlrev_b32_e32 v168, 16, v157
	v_and_b32_e32 v169, 0xffff0000, v157
	v_max_f32_e32 v168, 0xda24260, v168
	v_max_f32_e32 v169, 0xda24260, v169
	v_rcp_f32_e32 v168, v168
	v_rcp_f32_e32 v169, v169
	v_lshlrev_b32_e32 v166, 16, v147
	v_and_b32_e32 v167, 0xffff0000, v147
	v_pk_mul_f32 v[166:167], v[168:169], v[166:167]
	v_pk_mul_f32 v[74:75], v[74:75], v[166:167]
	v_lshlrev_b32_e32 v168, 16, v158
	v_and_b32_e32 v169, 0xffff0000, v158
	v_max_f32_e32 v168, 0xda24260, v168
	v_max_f32_e32 v169, 0xda24260, v169
	v_rcp_f32_e32 v168, v168
	v_rcp_f32_e32 v169, v169
	v_lshlrev_b32_e32 v166, 16, v148
	v_and_b32_e32 v167, 0xffff0000, v148
	v_pk_mul_f32 v[166:167], v[168:169], v[166:167]
	v_pk_mul_f32 v[68:69], v[68:69], v[166:167]
	v_lshlrev_b32_e32 v168, 16, v159
	v_and_b32_e32 v169, 0xffff0000, v159
	v_max_f32_e32 v168, 0xda24260, v168
	v_max_f32_e32 v169, 0xda24260, v169
	v_rcp_f32_e32 v168, v168
	v_rcp_f32_e32 v169, v169
	v_lshlrev_b32_e32 v166, 16, v149
	v_and_b32_e32 v167, 0xffff0000, v149
	v_pk_mul_f32 v[166:167], v[168:169], v[166:167]
	v_pk_mul_f32 v[70:71], v[70:71], v[166:167]
	global_load_dwordx4 v[146:149], v[160:161], off offset:256
	global_load_dwordx4 v[156:159], v[150:151], off offset:256
	s_waitcnt vmcnt(14)
	v_lshlrev_b32_e32 v168, 16, v194
	v_and_b32_e32 v169, 0xffff0000, v194
	v_max_f32_e32 v168, 0xda24260, v168
	v_max_f32_e32 v169, 0xda24260, v169
	v_rcp_f32_e32 v168, v168
	v_rcp_f32_e32 v169, v169
	v_lshlrev_b32_e32 v166, 16, v190
	v_and_b32_e32 v167, 0xffff0000, v190
	v_pk_mul_f32 v[166:167], v[168:169], v[166:167]
	v_pk_mul_f32 v[64:65], v[64:65], v[166:167]
	v_lshlrev_b32_e32 v168, 16, v195
	v_and_b32_e32 v169, 0xffff0000, v195
	v_max_f32_e32 v168, 0xda24260, v168
	v_max_f32_e32 v169, 0xda24260, v169
	v_rcp_f32_e32 v168, v168
	v_rcp_f32_e32 v169, v169
	v_lshlrev_b32_e32 v166, 16, v191
	v_and_b32_e32 v167, 0xffff0000, v191
	v_pk_mul_f32 v[166:167], v[168:169], v[166:167]
	v_pk_mul_f32 v[66:67], v[66:67], v[166:167]
	v_lshlrev_b32_e32 v168, 16, v196
	v_and_b32_e32 v169, 0xffff0000, v196
	v_max_f32_e32 v168, 0xda24260, v168
	v_max_f32_e32 v169, 0xda24260, v169
	v_rcp_f32_e32 v168, v168
	v_rcp_f32_e32 v169, v169
	v_lshlrev_b32_e32 v166, 16, v192
	v_and_b32_e32 v167, 0xffff0000, v192
	v_pk_mul_f32 v[166:167], v[168:169], v[166:167]
	v_pk_mul_f32 v[60:61], v[60:61], v[166:167]
	v_lshlrev_b32_e32 v168, 16, v197
	v_and_b32_e32 v169, 0xffff0000, v197
	v_max_f32_e32 v168, 0xda24260, v168
	v_max_f32_e32 v169, 0xda24260, v169
	v_rcp_f32_e32 v168, v168
	v_rcp_f32_e32 v169, v169
	v_lshlrev_b32_e32 v166, 16, v193
	v_and_b32_e32 v167, 0xffff0000, v193
	v_pk_mul_f32 v[166:167], v[168:169], v[166:167]
	v_pk_mul_f32 v[62:63], v[62:63], v[166:167]
	s_waitcnt vmcnt(12)
	v_lshlrev_b32_e32 v168, 16, v202
	v_and_b32_e32 v169, 0xffff0000, v202
	v_max_f32_e32 v168, 0xda24260, v168
	v_max_f32_e32 v169, 0xda24260, v169
	v_rcp_f32_e32 v168, v168
	v_rcp_f32_e32 v169, v169
	v_lshlrev_b32_e32 v166, 16, v198
	v_and_b32_e32 v167, 0xffff0000, v198
	v_pk_mul_f32 v[166:167], v[168:169], v[166:167]
	v_pk_mul_f32 v[32:33], v[32:33], v[166:167]
	v_lshlrev_b32_e32 v168, 16, v203
	v_and_b32_e32 v169, 0xffff0000, v203
	v_max_f32_e32 v168, 0xda24260, v168
	v_max_f32_e32 v169, 0xda24260, v169
	v_rcp_f32_e32 v168, v168
	v_rcp_f32_e32 v169, v169
	v_lshlrev_b32_e32 v166, 16, v199
	v_and_b32_e32 v167, 0xffff0000, v199
	v_pk_mul_f32 v[166:167], v[168:169], v[166:167]
	v_pk_mul_f32 v[34:35], v[34:35], v[166:167]
	v_lshlrev_b32_e32 v168, 16, v204
	v_and_b32_e32 v169, 0xffff0000, v204
	v_max_f32_e32 v168, 0xda24260, v168
	v_max_f32_e32 v169, 0xda24260, v169
	v_rcp_f32_e32 v168, v168
	v_rcp_f32_e32 v169, v169
	v_lshlrev_b32_e32 v166, 16, v200
	v_and_b32_e32 v167, 0xffff0000, v200
	v_pk_mul_f32 v[166:167], v[168:169], v[166:167]
	v_pk_mul_f32 v[28:29], v[28:29], v[166:167]
	v_lshlrev_b32_e32 v168, 16, v205
	v_and_b32_e32 v169, 0xffff0000, v205
	v_max_f32_e32 v168, 0xda24260, v168
	v_max_f32_e32 v169, 0xda24260, v169
	v_rcp_f32_e32 v168, v168
	v_rcp_f32_e32 v169, v169
	v_lshlrev_b32_e32 v166, 16, v201
	v_and_b32_e32 v167, 0xffff0000, v201
	v_pk_mul_f32 v[166:167], v[168:169], v[166:167]
	v_pk_mul_f32 v[30:31], v[30:31], v[166:167]
	s_waitcnt vmcnt(10)
	v_lshlrev_b32_e32 v168, 16, v210
	v_and_b32_e32 v169, 0xffff0000, v210
	v_max_f32_e32 v168, 0xda24260, v168
	v_max_f32_e32 v169, 0xda24260, v169
	v_rcp_f32_e32 v168, v168
	v_rcp_f32_e32 v169, v169
	v_lshlrev_b32_e32 v166, 16, v206
	v_and_b32_e32 v167, 0xffff0000, v206
	v_pk_mul_f32 v[166:167], v[168:169], v[166:167]
	v_pk_mul_f32 v[56:57], v[56:57], v[166:167]
	v_lshlrev_b32_e32 v168, 16, v211
	v_and_b32_e32 v169, 0xffff0000, v211
	v_max_f32_e32 v168, 0xda24260, v168
	v_max_f32_e32 v169, 0xda24260, v169
	v_rcp_f32_e32 v168, v168
	v_rcp_f32_e32 v169, v169
	v_lshlrev_b32_e32 v166, 16, v207
	v_and_b32_e32 v167, 0xffff0000, v207
	v_pk_mul_f32 v[166:167], v[168:169], v[166:167]
	v_pk_mul_f32 v[58:59], v[58:59], v[166:167]
	v_lshlrev_b32_e32 v168, 16, v212
	v_and_b32_e32 v169, 0xffff0000, v212
	v_max_f32_e32 v168, 0xda24260, v168
	v_max_f32_e32 v169, 0xda24260, v169
	v_rcp_f32_e32 v168, v168
	v_rcp_f32_e32 v169, v169
	v_lshlrev_b32_e32 v166, 16, v208
	v_and_b32_e32 v167, 0xffff0000, v208
	v_pk_mul_f32 v[166:167], v[168:169], v[166:167]
	v_pk_mul_f32 v[52:53], v[52:53], v[166:167]
	v_lshlrev_b32_e32 v168, 16, v213
	v_and_b32_e32 v169, 0xffff0000, v213
	v_max_f32_e32 v168, 0xda24260, v168
	v_max_f32_e32 v169, 0xda24260, v169
	v_rcp_f32_e32 v168, v168
	v_rcp_f32_e32 v169, v169
	v_lshlrev_b32_e32 v166, 16, v209
	v_and_b32_e32 v167, 0xffff0000, v209
	v_pk_mul_f32 v[166:167], v[168:169], v[166:167]
	v_pk_mul_f32 v[54:55], v[54:55], v[166:167]
	s_waitcnt vmcnt(8)
; __device__ __forceinline__ float lo16(unsigned u) { return __uint_as_float(u << 16); }
; __device__ __forceinline__ float hi16(unsigned u) { return __uint_as_float(u & 0xffff0000u); }
;   __device__ __forceinline__ bool operator()(f32x4 (&acc)[2][2][4][2], const Unit& u, int wr, int wc, int fr, int fq) const {
;     ...
;           const bf16_t* sp = pg + row * 8192 + (size_t)j * 2048 + col0 + bj * HALF;
;           const u32x4 sc = *(const u32x4*)sp;
;           float f[8] = {lo16(sc.x), hi16(sc.x), lo16(sc.y), hi16(sc.y), lo16(sc.z), hi16(sc.z), lo16(sc.w), hi16(sc.w)};
;           if (j < 3) { const u32x4 sn = *(const u32x4*)(sp + 2048);
;             float g[8] = {lo16(sn.x), hi16(sn.x), lo16(sn.y), hi16(sn.y), lo16(sn.z), hi16(sn.z), lo16(sn.w), hi16(sn.w)};
; #pragma unroll
;             for (int e = 0; e < 8; ++e) f[e] = f[e] * __builtin_amdgcn_rcpf(fmaxf(g[e], 1e-30f)); }
;           f32x4 v0 = acc[ai][bj][m][0], v1 = acc[ai][bj][m][1];
; #pragma unroll
;           for (int e = 0; e < 4; ++e) { v0[e] *= f[e]; v1[e] *= f[4 + e]; }
;           acc[ai][bj][m][0] = v0; acc[ai][bj][m][1] = v1;
	v_lshlrev_b32_e32 v168, 16, v218
	v_and_b32_e32 v169, 0xffff0000, v218
	v_max_f32_e32 v168, 0xda24260, v168
	v_max_f32_e32 v169, 0xda24260, v169
	v_rcp_f32_e32 v168, v168
	v_rcp_f32_e32 v169, v169
	v_lshlrev_b32_e32 v166, 16, v214
	v_and_b32_e32 v167, 0xffff0000, v214
	v_pk_mul_f32 v[166:167], v[168:169], v[166:167]
	v_pk_mul_f32 v[24:25], v[24:25], v[166:167]
	v_lshlrev_b32_e32 v168, 16, v219
	v_and_b32_e32 v169, 0xffff0000, v219
	v_max_f32_e32 v168, 0xda24260, v168
	v_max_f32_e32 v169, 0xda24260, v169
	v_rcp_f32_e32 v168, v168
	v_rcp_f32_e32 v169, v169
	v_lshlrev_b32_e32 v166, 16, v215
	v_and_b32_e32 v167, 0xffff0000, v215
	v_pk_mul_f32 v[166:167], v[168:169], v[166:167]
	v_pk_mul_f32 v[26:27], v[26:27], v[166:167]
	v_lshlrev_b32_e32 v168, 16, v220
	v_and_b32_e32 v169, 0xffff0000, v220
	v_max_f32_e32 v168, 0xda24260, v168
	v_max_f32_e32 v169, 0xda24260, v169
	v_rcp_f32_e32 v168, v168
	v_rcp_f32_e32 v169, v169
	v_lshlrev_b32_e32 v166, 16, v216
	v_and_b32_e32 v167, 0xffff0000, v216
	v_pk_mul_f32 v[166:167], v[168:169], v[166:167]
	v_pk_mul_f32 v[20:21], v[20:21], v[166:167]
	v_lshlrev_b32_e32 v168, 16, v221
	v_and_b32_e32 v169, 0xffff0000, v221
	v_max_f32_e32 v168, 0xda24260, v168
	v_max_f32_e32 v169, 0xda24260, v169
	v_rcp_f32_e32 v168, v168
	v_rcp_f32_e32 v169, v169
	v_lshlrev_b32_e32 v166, 16, v217
	v_and_b32_e32 v167, 0xffff0000, v217
	v_pk_mul_f32 v[166:167], v[168:169], v[166:167]
	v_pk_mul_f32 v[22:23], v[22:23], v[166:167]
	s_waitcnt vmcnt(6)
	v_lshlrev_b32_e32 v168, 16, v226
	v_and_b32_e32 v169, 0xffff0000, v226
	v_max_f32_e32 v168, 0xda24260, v168
	v_max_f32_e32 v169, 0xda24260, v169
	v_rcp_f32_e32 v168, v168
	v_rcp_f32_e32 v169, v169
	v_lshlrev_b32_e32 v166, 16, v222
	v_and_b32_e32 v167, 0xffff0000, v222
	v_pk_mul_f32 v[166:167], v[168:169], v[166:167]
	v_pk_mul_f32 v[48:49], v[48:49], v[166:167]
	v_lshlrev_b32_e32 v168, 16, v227
	v_and_b32_e32 v169, 0xffff0000, v227
	v_max_f32_e32 v168, 0xda24260, v168
	v_max_f32_e32 v169, 0xda24260, v169
	v_rcp_f32_e32 v168, v168
	v_rcp_f32_e32 v169, v169
	v_lshlrev_b32_e32 v166, 16, v223
	v_and_b32_e32 v167, 0xffff0000, v223
	v_pk_mul_f32 v[166:167], v[168:169], v[166:167]
	v_pk_mul_f32 v[50:51], v[50:51], v[166:167]
	v_lshlrev_b32_e32 v168, 16, v228
	v_and_b32_e32 v169, 0xffff0000, v228
	v_max_f32_e32 v168, 0xda24260, v168
	v_max_f32_e32 v169, 0xda24260, v169
	v_rcp_f32_e32 v168, v168
	v_rcp_f32_e32 v169, v169
	v_lshlrev_b32_e32 v166, 16, v224
	v_and_b32_e32 v167, 0xffff0000, v224
	v_pk_mul_f32 v[166:167], v[168:169], v[166:167]
	v_pk_mul_f32 v[44:45], v[44:45], v[166:167]
	v_lshlrev_b32_e32 v168, 16, v229
	v_and_b32_e32 v169, 0xffff0000, v229
	v_max_f32_e32 v168, 0xda24260, v168
	v_max_f32_e32 v169, 0xda24260, v169
	v_rcp_f32_e32 v168, v168
	v_rcp_f32_e32 v169, v169
	v_lshlrev_b32_e32 v166, 16, v225
	v_and_b32_e32 v167, 0xffff0000, v225
	v_pk_mul_f32 v[166:167], v[168:169], v[166:167]
	v_pk_mul_f32 v[46:47], v[46:47], v[166:167]
	s_waitcnt vmcnt(4)
	v_lshlrev_b32_e32 v168, 16, v234
	v_and_b32_e32 v169, 0xffff0000, v234
	v_max_f32_e32 v168, 0xda24260, v168
	v_max_f32_e32 v169, 0xda24260, v169
	v_rcp_f32_e32 v168, v168
	v_rcp_f32_e32 v169, v169
	v_lshlrev_b32_e32 v166, 16, v230
	v_and_b32_e32 v167, 0xffff0000, v230
	v_pk_mul_f32 v[166:167], v[168:169], v[166:167]
	v_pk_mul_f32 v[16:17], v[16:17], v[166:167]
	v_lshlrev_b32_e32 v168, 16, v235
	v_and_b32_e32 v169, 0xffff0000, v235
	v_max_f32_e32 v168, 0xda24260, v168
	v_max_f32_e32 v169, 0xda24260, v169
	v_rcp_f32_e32 v168, v168
	v_rcp_f32_e32 v169, v169
	v_lshlrev_b32_e32 v166, 16, v231
	v_and_b32_e32 v167, 0xffff0000, v231
	v_pk_mul_f32 v[166:167], v[168:169], v[166:167]
	v_pk_mul_f32 v[18:19], v[18:19], v[166:167]
	v_lshlrev_b32_e32 v168, 16, v236
	v_and_b32_e32 v169, 0xffff0000, v236
	v_max_f32_e32 v168, 0xda24260, v168
	v_max_f32_e32 v169, 0xda24260, v169
	v_rcp_f32_e32 v168, v168
	v_rcp_f32_e32 v169, v169
	v_lshlrev_b32_e32 v166, 16, v232
	v_and_b32_e32 v167, 0xffff0000, v232
	v_pk_mul_f32 v[166:167], v[168:169], v[166:167]
	v_pk_mul_f32 v[12:13], v[12:13], v[166:167]
	v_lshlrev_b32_e32 v168, 16, v237
	v_and_b32_e32 v169, 0xffff0000, v237
	v_max_f32_e32 v168, 0xda24260, v168
	v_max_f32_e32 v169, 0xda24260, v169
	v_rcp_f32_e32 v168, v168
	v_rcp_f32_e32 v169, v169
	v_lshlrev_b32_e32 v166, 16, v233
	v_and_b32_e32 v167, 0xffff0000, v233
	v_pk_mul_f32 v[166:167], v[168:169], v[166:167]
	v_pk_mul_f32 v[14:15], v[14:15], v[166:167]
	s_waitcnt vmcnt(2)
	v_lshlrev_b32_e32 v168, 16, v142
	v_and_b32_e32 v169, 0xffff0000, v142
	v_max_f32_e32 v168, 0xda24260, v168
	v_max_f32_e32 v169, 0xda24260, v169
	v_rcp_f32_e32 v168, v168
	v_rcp_f32_e32 v169, v169
	v_lshlrev_b32_e32 v166, 16, v238
	v_and_b32_e32 v167, 0xffff0000, v238
	v_pk_mul_f32 v[166:167], v[168:169], v[166:167]
	v_pk_mul_f32 v[40:41], v[40:41], v[166:167]
	v_lshlrev_b32_e32 v168, 16, v143
	v_and_b32_e32 v169, 0xffff0000, v143
	v_max_f32_e32 v168, 0xda24260, v168
	v_max_f32_e32 v169, 0xda24260, v169
	v_rcp_f32_e32 v168, v168
	v_rcp_f32_e32 v169, v169
	v_lshlrev_b32_e32 v166, 16, v239
	v_and_b32_e32 v167, 0xffff0000, v239
	v_pk_mul_f32 v[166:167], v[168:169], v[166:167]
	v_pk_mul_f32 v[42:43], v[42:43], v[166:167]
	v_lshlrev_b32_e32 v168, 16, v144
	v_and_b32_e32 v169, 0xffff0000, v144
	v_max_f32_e32 v168, 0xda24260, v168
	v_max_f32_e32 v169, 0xda24260, v169
	v_rcp_f32_e32 v168, v168
	v_rcp_f32_e32 v169, v169
	v_lshlrev_b32_e32 v166, 16, v240
	v_and_b32_e32 v167, 0xffff0000, v240
	v_pk_mul_f32 v[166:167], v[168:169], v[166:167]
	v_pk_mul_f32 v[36:37], v[36:37], v[166:167]
	v_lshlrev_b32_e32 v168, 16, v145
	v_and_b32_e32 v169, 0xffff0000, v145
	v_max_f32_e32 v168, 0xda24260, v168
	v_max_f32_e32 v169, 0xda24260, v169
	v_rcp_f32_e32 v168, v168
	v_rcp_f32_e32 v169, v169
	v_lshlrev_b32_e32 v166, 16, v241
	v_and_b32_e32 v167, 0xffff0000, v241
	v_pk_mul_f32 v[166:167], v[168:169], v[166:167]
	v_pk_mul_f32 v[38:39], v[38:39], v[166:167]
	s_waitcnt vmcnt(0)
; __device__ __forceinline__ float lo16(unsigned u) { return __uint_as_float(u << 16); }
; __device__ __forceinline__ float hi16(unsigned u) { return __uint_as_float(u & 0xffff0000u); }
; __device__ __forceinline__ unsigned pk2(float lo, float hi) { f32x2n v = {lo, hi}; bf16x2n b = __builtin_convertvector(v, bf16x2n); return __builtin_bit_cast(unsigned, b); }
;   __device__ __forceinline__ bool operator()(f32x4 (&acc)[2][2][4][2], const Unit& u, int wr, int wc, int fr, int fq) const {
;     ...
;           const bf16_t* sp = pg + row * 8192 + (size_t)j * 2048 + col0 + bj * HALF;
;           const u32x4 sc = *(const u32x4*)sp;
;           float f[8] = {lo16(sc.x), hi16(sc.x), lo16(sc.y), hi16(sc.y), lo16(sc.z), hi16(sc.z), lo16(sc.w), hi16(sc.w)};
;           if (j < 3) { const u32x4 sn = *(const u32x4*)(sp + 2048);
;             float g[8] = {lo16(sn.x), hi16(sn.x), lo16(sn.y), hi16(sn.y), lo16(sn.z), hi16(sn.z), lo16(sn.w), hi16(sn.w)};
; #pragma unroll
;             for (int e = 0; e < 8; ++e) f[e] = f[e] * __builtin_amdgcn_rcpf(fmaxf(g[e], 1e-30f)); }
;           f32x4 v0 = acc[ai][bj][m][0], v1 = acc[ai][bj][m][1];
; #pragma unroll
;           for (int e = 0; e < 4; ++e) { v0[e] *= f[e]; v1[e] *= f[4 + e]; }
;           acc[ai][bj][m][0] = v0; acc[ai][bj][m][1] = v1;
;           if (j == 3) { u32x4 w; w.x = pk2(v0[0], v0[1]); w.y = pk2(v0[2], v0[3]); w.z = pk2(v1[0], v1[1]); w.w = pk2(v1[2], v1[3]);
;             *(u32x4*)(mo + row * 2048 + col0 + bj * HALF) = w; } } }
	v_lshlrev_b32_e32 v168, 16, v156
	v_and_b32_e32 v169, 0xffff0000, v156
	v_max_f32_e32 v168, 0xda24260, v168
	v_max_f32_e32 v169, 0xda24260, v169
	v_rcp_f32_e32 v168, v168
	v_rcp_f32_e32 v169, v169
	v_lshlrev_b32_e32 v166, 16, v146
	v_and_b32_e32 v167, 0xffff0000, v146
	v_pk_mul_f32 v[166:167], v[168:169], v[166:167]
	v_pk_mul_f32 v[8:9], v[8:9], v[166:167]
	v_lshlrev_b32_e32 v168, 16, v157
	v_and_b32_e32 v169, 0xffff0000, v157
	v_max_f32_e32 v168, 0xda24260, v168
	v_max_f32_e32 v169, 0xda24260, v169
	v_rcp_f32_e32 v168, v168
	v_rcp_f32_e32 v169, v169
	v_lshlrev_b32_e32 v166, 16, v147
	v_and_b32_e32 v167, 0xffff0000, v147
	v_pk_mul_f32 v[166:167], v[168:169], v[166:167]
	v_pk_mul_f32 v[10:11], v[10:11], v[166:167]
	v_lshlrev_b32_e32 v168, 16, v158
	v_and_b32_e32 v169, 0xffff0000, v158
	v_max_f32_e32 v168, 0xda24260, v168
	v_max_f32_e32 v169, 0xda24260, v169
	v_rcp_f32_e32 v168, v168
	v_rcp_f32_e32 v169, v169
	v_lshlrev_b32_e32 v166, 16, v148
	v_and_b32_e32 v167, 0xffff0000, v148
	v_pk_mul_f32 v[166:167], v[168:169], v[166:167]
	v_pk_mul_f32 v[4:5], v[4:5], v[166:167]
	v_lshlrev_b32_e32 v168, 16, v159
	v_and_b32_e32 v169, 0xffff0000, v159
	v_max_f32_e32 v168, 0xda24260, v168
	v_max_f32_e32 v169, 0xda24260, v169
	v_rcp_f32_e32 v168, v168
	v_rcp_f32_e32 v169, v169
	v_lshlrev_b32_e32 v166, 16, v149
	v_and_b32_e32 v167, 0xffff0000, v149
	v_pk_mul_f32 v[166:167], v[168:169], v[166:167]
	v_pk_mul_f32 v[6:7], v[6:7], v[166:167]
	s_branch .Lg2e_done
.Lg2e_eq3:
	s_lshl_b32 s11, s12, 20
	s_add_u32 s30, s18, s11
	s_addc_u32 s31, s19, 0
	s_add_u32 s30, s30, s13
	s_addc_u32 s31, s31, 0
	v_lshl_add_u32 v150, v3, 12, v165
	v_mov_b32_e32 v151, 0
	v_lshl_add_u64 v[150:151], v[150:151], 0, s[30:31]
	global_load_dwordx4 v[190:193], v[160:161], off
	global_load_dwordx4 v[194:197], v[160:161], off offset:256
	v_lshl_add_u64 v[160:161], v[160:161], 0, s[28:29]
	global_load_dwordx4 v[198:201], v[160:161], off
	global_load_dwordx4 v[202:205], v[160:161], off offset:256
	v_lshl_add_u64 v[160:161], v[160:161], 0, s[28:29]
	global_load_dwordx4 v[206:209], v[160:161], off
	global_load_dwordx4 v[210:213], v[160:161], off offset:256
	v_lshl_add_u64 v[160:161], v[160:161], 0, s[28:29]
	global_load_dwordx4 v[214:217], v[160:161], off
	global_load_dwordx4 v[218:221], v[160:161], off offset:256
	s_mov_b32 s28, 0x140000
	v_lshl_add_u64 v[160:161], v[160:161], 0, s[28:29]
	s_mov_b32 s28, 0x40000
	global_load_dwordx4 v[222:225], v[160:161], off
	global_load_dwordx4 v[226:229], v[160:161], off offset:256
	v_lshl_add_u64 v[160:161], v[160:161], 0, s[28:29]
	global_load_dwordx4 v[230:233], v[160:161], off
	global_load_dwordx4 v[234:237], v[160:161], off offset:256
	v_lshl_add_u64 v[160:161], v[160:161], 0, s[28:29]
	global_load_dwordx4 v[238:241], v[160:161], off
	global_load_dwordx4 v[142:145], v[160:161], off offset:256
	v_lshl_add_u64 v[160:161], v[160:161], 0, s[28:29]
	global_load_dwordx4 v[146:149], v[160:161], off
	global_load_dwordx4 v[156:159], v[160:161], off offset:256
	s_mov_b32 s28, 0x10000
	s_waitcnt vmcnt(15)
	v_lshlrev_b32_e32 v166, 16, v190
	v_and_b32_e32 v167, 0xffff0000, v190
	v_pk_mul_f32 v[128:129], v[128:129], v[166:167]
	v_cvt_pk_bf16_f32 v190, v128, v129
	v_lshlrev_b32_e32 v166, 16, v191
	v_and_b32_e32 v167, 0xffff0000, v191
	v_pk_mul_f32 v[130:131], v[130:131], v[166:167]
	v_cvt_pk_bf16_f32 v191, v130, v131
	v_lshlrev_b32_e32 v166, 16, v192
	v_and_b32_e32 v167, 0xffff0000, v192
	v_pk_mul_f32 v[124:125], v[124:125], v[166:167]
	v_cvt_pk_bf16_f32 v192, v124, v125
	v_lshlrev_b32_e32 v166, 16, v193
	v_and_b32_e32 v167, 0xffff0000, v193
	v_pk_mul_f32 v[126:127], v[126:127], v[166:167]
	v_cvt_pk_bf16_f32 v193, v126, v127
	global_store_dwordx4 v[150:151], v[190:193], off
	s_waitcnt vmcnt(15)
	v_lshlrev_b32_e32 v166, 16, v194
	v_and_b32_e32 v167, 0xffff0000, v194
	v_pk_mul_f32 v[96:97], v[96:97], v[166:167]
	v_cvt_pk_bf16_f32 v194, v96, v97
	v_lshlrev_b32_e32 v166, 16, v195
	v_and_b32_e32 v167, 0xffff0000, v195
	v_pk_mul_f32 v[98:99], v[98:99], v[166:167]
	v_cvt_pk_bf16_f32 v195, v98, v99
	v_lshlrev_b32_e32 v166, 16, v196
	v_and_b32_e32 v167, 0xffff0000, v196
	v_pk_mul_f32 v[92:93], v[92:93], v[166:167]
	v_cvt_pk_bf16_f32 v196, v92, v93
	v_lshlrev_b32_e32 v166, 16, v197
	v_and_b32_e32 v167, 0xffff0000, v197
	v_pk_mul_f32 v[94:95], v[94:95], v[166:167]
	v_cvt_pk_bf16_f32 v197, v94, v95
	global_store_dwordx4 v[150:151], v[194:197], off offset:256
	v_lshl_add_u64 v[150:151], v[150:151], 0, s[28:29]
	s_waitcnt vmcnt(15)
	v_lshlrev_b32_e32 v166, 16, v198
	v_and_b32_e32 v167, 0xffff0000, v198
	v_pk_mul_f32 v[120:121], v[120:121], v[166:167]
	v_cvt_pk_bf16_f32 v198, v120, v121
	v_lshlrev_b32_e32 v166, 16, v199
	v_and_b32_e32 v167, 0xffff0000, v199
	v_pk_mul_f32 v[122:123], v[122:123], v[166:167]
	v_cvt_pk_bf16_f32 v199, v122, v123
	v_lshlrev_b32_e32 v166, 16, v200
	v_and_b32_e32 v167, 0xffff0000, v200
	v_pk_mul_f32 v[116:117], v[116:117], v[166:167]
	v_cvt_pk_bf16_f32 v200, v116, v117
	v_lshlrev_b32_e32 v166, 16, v201
	v_and_b32_e32 v167, 0xffff0000, v201
	v_pk_mul_f32 v[118:119], v[118:119], v[166:167]
	v_cvt_pk_bf16_f32 v201, v118, v119
	global_store_dwordx4 v[150:151], v[198:201], off
	s_waitcnt vmcnt(15)
	v_lshlrev_b32_e32 v166, 16, v202
	v_and_b32_e32 v167, 0xffff0000, v202
	v_pk_mul_f32 v[88:89], v[88:89], v[166:167]
	v_cvt_pk_bf16_f32 v202, v88, v89
	v_lshlrev_b32_e32 v166, 16, v203
	v_and_b32_e32 v167, 0xffff0000, v203
	v_pk_mul_f32 v[90:91], v[90:91], v[166:167]
	v_cvt_pk_bf16_f32 v203, v90, v91
	v_lshlrev_b32_e32 v166, 16, v204
	v_and_b32_e32 v167, 0xffff0000, v204
	v_pk_mul_f32 v[84:85], v[84:85], v[166:167]
	v_cvt_pk_bf16_f32 v204, v84, v85
	v_lshlrev_b32_e32 v166, 16, v205
	v_and_b32_e32 v167, 0xffff0000, v205
	v_pk_mul_f32 v[86:87], v[86:87], v[166:167]
	v_cvt_pk_bf16_f32 v205, v86, v87
	global_store_dwordx4 v[150:151], v[202:205], off offset:256
	v_lshl_add_u64 v[150:151], v[150:151], 0, s[28:29]
	s_waitcnt vmcnt(15)
; __device__ __forceinline__ unsigned pk2(float lo, float hi) { f32x2n v = {lo, hi}; bf16x2n b = __builtin_convertvector(v, bf16x2n); return __builtin_bit_cast(unsigned, b); }
;   __device__ __forceinline__ bool operator()(f32x4 (&acc)[2][2][4][2], const Unit& u, int wr, int wc, int fr, int fq) const {
;     ...
;           f32x4 v0 = acc[ai][bj][m][0], v1 = acc[ai][bj][m][1];
; #pragma unroll
;           for (int e = 0; e < 4; ++e) { v0[e] *= f[e]; v1[e] *= f[4 + e]; }
;           acc[ai][bj][m][0] = v0; acc[ai][bj][m][1] = v1;
;           if (j == 3) { u32x4 w; w.x = pk2(v0[0], v0[1]); w.y = pk2(v0[2], v0[3]); w.z = pk2(v1[0], v1[1]); w.w = pk2(v1[2], v1[3]);
;             *(u32x4*)(mo + row * 2048 + col0 + bj * HALF) = w; } } }
	v_lshlrev_b32_e32 v166, 16, v206
	v_and_b32_e32 v167, 0xffff0000, v206
	v_pk_mul_f32 v[112:113], v[112:113], v[166:167]
	v_cvt_pk_bf16_f32 v206, v112, v113
	v_lshlrev_b32_e32 v166, 16, v207
	v_and_b32_e32 v167, 0xffff0000, v207
	v_pk_mul_f32 v[114:115], v[114:115], v[166:167]
	v_cvt_pk_bf16_f32 v207, v114, v115
	v_lshlrev_b32_e32 v166, 16, v208
	v_and_b32_e32 v167, 0xffff0000, v208
	v_pk_mul_f32 v[108:109], v[108:109], v[166:167]
	v_cvt_pk_bf16_f32 v208, v108, v109
	v_lshlrev_b32_e32 v166, 16, v209
	v_and_b32_e32 v167, 0xffff0000, v209
	v_pk_mul_f32 v[110:111], v[110:111], v[166:167]
	v_cvt_pk_bf16_f32 v209, v110, v111
	global_store_dwordx4 v[150:151], v[206:209], off
	s_waitcnt vmcnt(15)
	v_lshlrev_b32_e32 v166, 16, v210
	v_and_b32_e32 v167, 0xffff0000, v210
	v_pk_mul_f32 v[80:81], v[80:81], v[166:167]
	v_cvt_pk_bf16_f32 v210, v80, v81
	v_lshlrev_b32_e32 v166, 16, v211
	v_and_b32_e32 v167, 0xffff0000, v211
	v_pk_mul_f32 v[82:83], v[82:83], v[166:167]
	v_cvt_pk_bf16_f32 v211, v82, v83
	v_lshlrev_b32_e32 v166, 16, v212
	v_and_b32_e32 v167, 0xffff0000, v212
	v_pk_mul_f32 v[76:77], v[76:77], v[166:167]
	v_cvt_pk_bf16_f32 v212, v76, v77
	v_lshlrev_b32_e32 v166, 16, v213
	v_and_b32_e32 v167, 0xffff0000, v213
	v_pk_mul_f32 v[78:79], v[78:79], v[166:167]
	v_cvt_pk_bf16_f32 v213, v78, v79
	global_store_dwordx4 v[150:151], v[210:213], off offset:256
	v_lshl_add_u64 v[150:151], v[150:151], 0, s[28:29]
	s_waitcnt vmcnt(15)
	v_lshlrev_b32_e32 v166, 16, v214
	v_and_b32_e32 v167, 0xffff0000, v214
	v_pk_mul_f32 v[104:105], v[104:105], v[166:167]
	v_cvt_pk_bf16_f32 v214, v104, v105
	v_lshlrev_b32_e32 v166, 16, v215
	v_and_b32_e32 v167, 0xffff0000, v215
	v_pk_mul_f32 v[106:107], v[106:107], v[166:167]
	v_cvt_pk_bf16_f32 v215, v106, v107
	v_lshlrev_b32_e32 v166, 16, v216
	v_and_b32_e32 v167, 0xffff0000, v216
	v_pk_mul_f32 v[100:101], v[100:101], v[166:167]
	v_cvt_pk_bf16_f32 v216, v100, v101
	v_lshlrev_b32_e32 v166, 16, v217
	v_and_b32_e32 v167, 0xffff0000, v217
	v_pk_mul_f32 v[102:103], v[102:103], v[166:167]
	v_cvt_pk_bf16_f32 v217, v102, v103
	global_store_dwordx4 v[150:151], v[214:217], off
	s_waitcnt vmcnt(15)
	v_lshlrev_b32_e32 v166, 16, v218
	v_and_b32_e32 v167, 0xffff0000, v218
	v_pk_mul_f32 v[72:73], v[72:73], v[166:167]
	v_cvt_pk_bf16_f32 v218, v72, v73
	v_lshlrev_b32_e32 v166, 16, v219
	v_and_b32_e32 v167, 0xffff0000, v219
	v_pk_mul_f32 v[74:75], v[74:75], v[166:167]
	v_cvt_pk_bf16_f32 v219, v74, v75
	v_lshlrev_b32_e32 v166, 16, v220
	v_and_b32_e32 v167, 0xffff0000, v220
	v_pk_mul_f32 v[68:69], v[68:69], v[166:167]
	v_cvt_pk_bf16_f32 v220, v68, v69
	v_lshlrev_b32_e32 v166, 16, v221
	v_and_b32_e32 v167, 0xffff0000, v221
	v_pk_mul_f32 v[70:71], v[70:71], v[166:167]
	v_cvt_pk_bf16_f32 v221, v70, v71
	global_store_dwordx4 v[150:151], v[218:221], off offset:256
	s_mov_b32 s28, 0x50000
	v_lshl_add_u64 v[150:151], v[150:151], 0, s[28:29]
	s_mov_b32 s28, 0x10000
	s_waitcnt vmcnt(15)
	v_lshlrev_b32_e32 v166, 16, v222
	v_and_b32_e32 v167, 0xffff0000, v222
	v_pk_mul_f32 v[64:65], v[64:65], v[166:167]
	v_cvt_pk_bf16_f32 v222, v64, v65
	v_lshlrev_b32_e32 v166, 16, v223
	v_and_b32_e32 v167, 0xffff0000, v223
	v_pk_mul_f32 v[66:67], v[66:67], v[166:167]
	v_cvt_pk_bf16_f32 v223, v66, v67
	v_lshlrev_b32_e32 v166, 16, v224
	v_and_b32_e32 v167, 0xffff0000, v224
	v_pk_mul_f32 v[60:61], v[60:61], v[166:167]
	v_cvt_pk_bf16_f32 v224, v60, v61
	v_lshlrev_b32_e32 v166, 16, v225
	v_and_b32_e32 v167, 0xffff0000, v225
	v_pk_mul_f32 v[62:63], v[62:63], v[166:167]
	v_cvt_pk_bf16_f32 v225, v62, v63
	global_store_dwordx4 v[150:151], v[222:225], off
	s_waitcnt vmcnt(15)
	v_lshlrev_b32_e32 v166, 16, v226
	v_and_b32_e32 v167, 0xffff0000, v226
	v_pk_mul_f32 v[32:33], v[32:33], v[166:167]
	v_cvt_pk_bf16_f32 v226, v32, v33
	v_lshlrev_b32_e32 v166, 16, v227
	v_and_b32_e32 v167, 0xffff0000, v227
	v_pk_mul_f32 v[34:35], v[34:35], v[166:167]
	v_cvt_pk_bf16_f32 v227, v34, v35
	v_lshlrev_b32_e32 v166, 16, v228
	v_and_b32_e32 v167, 0xffff0000, v228
	v_pk_mul_f32 v[28:29], v[28:29], v[166:167]
	v_cvt_pk_bf16_f32 v228, v28, v29
	v_lshlrev_b32_e32 v166, 16, v229
	v_and_b32_e32 v167, 0xffff0000, v229
	v_pk_mul_f32 v[30:31], v[30:31], v[166:167]
	v_cvt_pk_bf16_f32 v229, v30, v31
	global_store_dwordx4 v[150:151], v[226:229], off offset:256
	v_lshl_add_u64 v[150:151], v[150:151], 0, s[28:29]
	s_waitcnt vmcnt(15)
; __device__ __forceinline__ unsigned pk2(float lo, float hi) { f32x2n v = {lo, hi}; bf16x2n b = __builtin_convertvector(v, bf16x2n); return __builtin_bit_cast(unsigned, b); }
;   __device__ __forceinline__ bool operator()(f32x4 (&acc)[2][2][4][2], const Unit& u, int wr, int wc, int fr, int fq) const {
;     ...
;           f32x4 v0 = acc[ai][bj][m][0], v1 = acc[ai][bj][m][1];
; #pragma unroll
;           for (int e = 0; e < 4; ++e) { v0[e] *= f[e]; v1[e] *= f[4 + e]; }
;           acc[ai][bj][m][0] = v0; acc[ai][bj][m][1] = v1;
;           if (j == 3) { u32x4 w; w.x = pk2(v0[0], v0[1]); w.y = pk2(v0[2], v0[3]); w.z = pk2(v1[0], v1[1]); w.w = pk2(v1[2], v1[3]);
;             *(u32x4*)(mo + row * 2048 + col0 + bj * HALF) = w; } } }
;     return j == 3;
	v_lshlrev_b32_e32 v166, 16, v230
	v_and_b32_e32 v167, 0xffff0000, v230
	v_pk_mul_f32 v[56:57], v[56:57], v[166:167]
	v_cvt_pk_bf16_f32 v230, v56, v57
	v_lshlrev_b32_e32 v166, 16, v231
	v_and_b32_e32 v167, 0xffff0000, v231
	v_pk_mul_f32 v[58:59], v[58:59], v[166:167]
	v_cvt_pk_bf16_f32 v231, v58, v59
	v_lshlrev_b32_e32 v166, 16, v232
	v_and_b32_e32 v167, 0xffff0000, v232
	v_pk_mul_f32 v[52:53], v[52:53], v[166:167]
	v_cvt_pk_bf16_f32 v232, v52, v53
	v_lshlrev_b32_e32 v166, 16, v233
	v_and_b32_e32 v167, 0xffff0000, v233
	v_pk_mul_f32 v[54:55], v[54:55], v[166:167]
	v_cvt_pk_bf16_f32 v233, v54, v55
	global_store_dwordx4 v[150:151], v[230:233], off
	s_waitcnt vmcnt(15)
	v_lshlrev_b32_e32 v166, 16, v234
	v_and_b32_e32 v167, 0xffff0000, v234
	v_pk_mul_f32 v[24:25], v[24:25], v[166:167]
	v_cvt_pk_bf16_f32 v234, v24, v25
	v_lshlrev_b32_e32 v166, 16, v235
	v_and_b32_e32 v167, 0xffff0000, v235
	v_pk_mul_f32 v[26:27], v[26:27], v[166:167]
	v_cvt_pk_bf16_f32 v235, v26, v27
	v_lshlrev_b32_e32 v166, 16, v236
	v_and_b32_e32 v167, 0xffff0000, v236
	v_pk_mul_f32 v[20:21], v[20:21], v[166:167]
	v_cvt_pk_bf16_f32 v236, v20, v21
	v_lshlrev_b32_e32 v166, 16, v237
	v_and_b32_e32 v167, 0xffff0000, v237
	v_pk_mul_f32 v[22:23], v[22:23], v[166:167]
	v_cvt_pk_bf16_f32 v237, v22, v23
	global_store_dwordx4 v[150:151], v[234:237], off offset:256
	v_lshl_add_u64 v[150:151], v[150:151], 0, s[28:29]
	s_waitcnt vmcnt(15)
	v_lshlrev_b32_e32 v166, 16, v238
	v_and_b32_e32 v167, 0xffff0000, v238
	v_pk_mul_f32 v[48:49], v[48:49], v[166:167]
	v_cvt_pk_bf16_f32 v238, v48, v49
	v_lshlrev_b32_e32 v166, 16, v239
	v_and_b32_e32 v167, 0xffff0000, v239
	v_pk_mul_f32 v[50:51], v[50:51], v[166:167]
	v_cvt_pk_bf16_f32 v239, v50, v51
	v_lshlrev_b32_e32 v166, 16, v240
	v_and_b32_e32 v167, 0xffff0000, v240
	v_pk_mul_f32 v[44:45], v[44:45], v[166:167]
	v_cvt_pk_bf16_f32 v240, v44, v45
	v_lshlrev_b32_e32 v166, 16, v241
	v_and_b32_e32 v167, 0xffff0000, v241
	v_pk_mul_f32 v[46:47], v[46:47], v[166:167]
	v_cvt_pk_bf16_f32 v241, v46, v47
	global_store_dwordx4 v[150:151], v[238:241], off
	s_waitcnt vmcnt(15)
	v_lshlrev_b32_e32 v166, 16, v142
	v_and_b32_e32 v167, 0xffff0000, v142
	v_pk_mul_f32 v[16:17], v[16:17], v[166:167]
	v_cvt_pk_bf16_f32 v142, v16, v17
	v_lshlrev_b32_e32 v166, 16, v143
	v_and_b32_e32 v167, 0xffff0000, v143
	v_pk_mul_f32 v[18:19], v[18:19], v[166:167]
	v_cvt_pk_bf16_f32 v143, v18, v19
	v_lshlrev_b32_e32 v166, 16, v144
	v_and_b32_e32 v167, 0xffff0000, v144
	v_pk_mul_f32 v[12:13], v[12:13], v[166:167]
	v_cvt_pk_bf16_f32 v144, v12, v13
	v_lshlrev_b32_e32 v166, 16, v145
	v_and_b32_e32 v167, 0xffff0000, v145
	v_pk_mul_f32 v[14:15], v[14:15], v[166:167]
	v_cvt_pk_bf16_f32 v145, v14, v15
	global_store_dwordx4 v[150:151], v[142:145], off offset:256
	v_lshl_add_u64 v[150:151], v[150:151], 0, s[28:29]
	s_waitcnt vmcnt(15)
	v_lshlrev_b32_e32 v166, 16, v146
	v_and_b32_e32 v167, 0xffff0000, v146
	v_pk_mul_f32 v[40:41], v[40:41], v[166:167]
	v_cvt_pk_bf16_f32 v146, v40, v41
	v_lshlrev_b32_e32 v166, 16, v147
	v_and_b32_e32 v167, 0xffff0000, v147
	v_pk_mul_f32 v[42:43], v[42:43], v[166:167]
	v_cvt_pk_bf16_f32 v147, v42, v43
	v_lshlrev_b32_e32 v166, 16, v148
	v_and_b32_e32 v167, 0xffff0000, v148
	v_pk_mul_f32 v[36:37], v[36:37], v[166:167]
	v_cvt_pk_bf16_f32 v148, v36, v37
	v_lshlrev_b32_e32 v166, 16, v149
	v_and_b32_e32 v167, 0xffff0000, v149
	v_pk_mul_f32 v[38:39], v[38:39], v[166:167]
	v_cvt_pk_bf16_f32 v149, v38, v39
	global_store_dwordx4 v[150:151], v[146:149], off
	s_waitcnt vmcnt(15)
	v_lshlrev_b32_e32 v166, 16, v156
	v_and_b32_e32 v167, 0xffff0000, v156
	v_pk_mul_f32 v[8:9], v[8:9], v[166:167]
	v_cvt_pk_bf16_f32 v156, v8, v9
	v_lshlrev_b32_e32 v166, 16, v157
	v_and_b32_e32 v167, 0xffff0000, v157
	v_pk_mul_f32 v[10:11], v[10:11], v[166:167]
	v_cvt_pk_bf16_f32 v157, v10, v11
	v_lshlrev_b32_e32 v166, 16, v158
	v_and_b32_e32 v167, 0xffff0000, v158
	v_pk_mul_f32 v[4:5], v[4:5], v[166:167]
	v_cvt_pk_bf16_f32 v158, v4, v5
	v_lshlrev_b32_e32 v166, 16, v159
	v_and_b32_e32 v167, 0xffff0000, v159
	v_pk_mul_f32 v[6:7], v[6:7], v[166:167]
	v_cvt_pk_bf16_f32 v159, v6, v7
	global_store_dwordx4 v[150:151], v[156:159], off offset:256
.Lg2e_done:
	s_cmp_lg_u32 s10, 3
	s_cselect_b64 s[10:11], -1, 0
